# scan consumer waves at s_setprio 3 (producer waves stay at 0)
# speedup vs baseline: 1.0081x; 1.0081x over previous
.LBB0_56:
	s_and_b64 s[4:5], s[42:43], exec
	s_mov_b32 s4, 0x1caf0000
	s_cselect_b32 s4, s4, 0x14af0000
	s_add_u32 s4, s30, s4
	s_addc_u32 s5, s31, 0
	s_lshl_b32 s6, s37, 1
	v_lshl_add_u32 v0, s64, 4, v58
	s_add_u32 s4, s4, s6
	s_addc_u32 s5, s5, 0
	v_ashrrev_i32_e32 v1, 31, v0
	s_waitcnt lgkmcnt(0)
	s_barrier
	v_lshl_add_u64 v[0:1], v[0:1], 1, s[4:5]
	s_and_b64 s[4:5], s[42:43], exec
	s_movk_i32 s4, 0x4000
	s_mov_b32 s28, 0
	s_cselect_b32 s85, 0, -1
	s_cselect_b32 s84, s4, 0xffffc000
	s_waitcnt vmcnt(0)
	v_mov_b32_e32 v6, 0
	v_mov_b32_e32 v4, v78
	v_mov_b32_e32 v5, v15
	v_mov_b32_e32 v7, 0
	v_mov_b32_e32 v8, 0
	v_mov_b32_e32 v9, 0
	v_lshlrev_b32_e32 v74, 4, v58
	v_add_u32_e32 v74, 0x22000, v74
	s_setprio 3
	v_mov_b32_e32 v10, v59
	v_mov_b32_e32 v11, v74
	ds_read_b128 v[66:69], v11 offset:0
	ds_read_b128 v[20:23], v10 offset:256
	ds_read_b128 v[28:31], v10 offset:768
	ds_read_b128 v[24:27], v10 offset:512
	ds_read_b128 v[36:39], v10 offset:1280
	ds_read_b128 v[44:47], v10 offset:1792
	ds_read_b128 v[40:43], v10 offset:1536
.Lscan_cons_chunk:
	v_cndmask_b32_e64 v2, v4, v5, s[42:43]
	v_add_lshl_u32 v2, v2, s80, 10
	v_mov_b32_e32 v3, v180
	s_add_i32 s28, s28, 0x10000
	v_lshl_add_u64 v[2:3], v[0:1], 0, v[2:3]
	v_add_u32_e32 v5, 64, v5
	v_subrev_u32_e32 v4, 64, v4
	s_waitcnt lgkmcnt(3)
	v_fma_mix_f32 v12, v6, v20, v180 op_sel_hi:[0,1,0]
	v_fma_mix_f32 v12, v7, v20, v12 op_sel:[0,1,0] op_sel_hi:[0,1,0]
	v_fma_mix_f32 v12, v8, v21, v12 op_sel_hi:[0,1,0]
	v_fma_mix_f32 v12, v9, v21, v12 op_sel:[0,1,0] op_sel_hi:[0,1,0]
	s_nop 1
	v_add_f32_dpp v12, v12, v12 row_ror:1 row_mask:0xf bank_mask:0xf bound_ctrl:1
	s_nop 1
	v_add_f32_dpp v12, v12, v12 row_ror:2 row_mask:0xf bank_mask:0xf bound_ctrl:1
	v_pk_fma_f32 v[48:49], v[28:29], v[66:67], v[6:7] op_sel_hi:[1,0,1]
	v_pk_fma_f32 v[50:51], v[30:31], v[66:67], v[8:9] op_sel_hi:[1,0,1]
	v_add_f32_dpp v12, v12, v12 row_ror:4 row_mask:0xf bank_mask:0xf bound_ctrl:1
	s_nop 1
	v_add_f32_dpp v12, v12, v12 row_ror:8 row_mask:0xf bank_mask:0xf bound_ctrl:1
	v_pk_fma_f32 v[6:7], v[24:25], v[12:13], v[48:49] op_sel_hi:[1,0,1] neg_lo:[1,0,0] neg_hi:[1,0,0]
	v_pk_fma_f32 v[8:9], v[26:27], v[12:13], v[50:51] op_sel_hi:[1,0,1] neg_lo:[1,0,0] neg_hi:[1,0,0]
	ds_read_b128 v[88:91], v10 offset:2304
	ds_read_b128 v[96:99], v10 offset:2816
	ds_read_b128 v[92:95], v10 offset:2560
	s_waitcnt lgkmcnt(3)
	v_fma_mix_f32 v12, v6, v36, v180 op_sel_hi:[0,1,0]
	v_fma_mix_f32 v12, v7, v36, v12 op_sel:[0,1,0] op_sel_hi:[0,1,0]
	v_fma_mix_f32 v12, v8, v37, v12 op_sel_hi:[0,1,0]
	v_fma_mix_f32 v12, v9, v37, v12 op_sel:[0,1,0] op_sel_hi:[0,1,0]
	v_fma_mix_f32 v52, v6, v22, v180 op_sel_hi:[0,1,0]
	v_fma_mix_f32 v52, v7, v22, v52 op_sel:[0,1,0] op_sel_hi:[0,1,0]
	v_add_f32_dpp v12, v12, v12 row_ror:1 row_mask:0xf bank_mask:0xf bound_ctrl:1
	v_fma_mix_f32 v52, v8, v23, v52 op_sel_hi:[0,1,0]
	v_fma_mix_f32 v52, v9, v23, v52 op_sel:[0,1,0] op_sel_hi:[0,1,0]
	v_add_f32_dpp v12, v12, v12 row_ror:2 row_mask:0xf bank_mask:0xf bound_ctrl:1
	v_pk_fma_f32 v[48:49], v[44:45], v[66:67], v[6:7] op_sel:[0,1,0]
	v_pk_fma_f32 v[50:51], v[46:47], v[66:67], v[8:9] op_sel:[0,1,0]
	v_add_f32_dpp v12, v12, v12 row_ror:4 row_mask:0xf bank_mask:0xf bound_ctrl:1
	s_nop 1
	v_add_f32_dpp v12, v12, v12 row_ror:8 row_mask:0xf bank_mask:0xf bound_ctrl:1
	v_pk_fma_f32 v[6:7], v[40:41], v[12:13], v[48:49] op_sel_hi:[1,0,1] neg_lo:[1,0,0] neg_hi:[1,0,0]
	v_pk_fma_f32 v[8:9], v[42:43], v[12:13], v[50:51] op_sel_hi:[1,0,1] neg_lo:[1,0,0] neg_hi:[1,0,0]
	ds_read_b128 v[110:113], v10 offset:3328
	ds_read_b128 v[106:109], v10 offset:3072
	ds_read_b128 v[118:121], v10 offset:3840
	ds_read_b128 v[114:117], v10 offset:3584
	ds_read_b128 v[70:73], v11 offset:256
	s_waitcnt lgkmcnt(5)
	v_fma_mix_f32 v12, v6, v88, v180 op_sel_hi:[0,1,0]
	v_fma_mix_f32 v12, v7, v88, v12 op_sel:[0,1,0] op_sel_hi:[0,1,0]
	v_fma_mix_f32 v12, v8, v89, v12 op_sel_hi:[0,1,0]
	v_fma_mix_f32 v12, v9, v89, v12 op_sel:[0,1,0] op_sel_hi:[0,1,0]
	v_fma_mix_f32 v53, v6, v38, v180 op_sel_hi:[0,1,0]
	v_fma_mix_f32 v53, v7, v38, v53 op_sel:[0,1,0] op_sel_hi:[0,1,0]
	v_add_f32_dpp v12, v12, v12 row_ror:1 row_mask:0xf bank_mask:0xf bound_ctrl:1
	v_fma_mix_f32 v53, v8, v39, v53 op_sel_hi:[0,1,0]
	v_fma_mix_f32 v53, v9, v39, v53 op_sel:[0,1,0] op_sel_hi:[0,1,0]
	v_add_f32_dpp v12, v12, v12 row_ror:2 row_mask:0xf bank_mask:0xf bound_ctrl:1
	v_pk_fma_f32 v[48:49], v[96:97], v[68:69], v[6:7] op_sel_hi:[1,0,1]
	v_pk_fma_f32 v[50:51], v[98:99], v[68:69], v[8:9] op_sel_hi:[1,0,1]
	v_add_f32_dpp v12, v12, v12 row_ror:4 row_mask:0xf bank_mask:0xf bound_ctrl:1
	s_nop 1
	v_add_f32_dpp v12, v12, v12 row_ror:8 row_mask:0xf bank_mask:0xf bound_ctrl:1
	v_pk_fma_f32 v[6:7], v[92:93], v[12:13], v[48:49] op_sel_hi:[1,0,1] neg_lo:[1,0,0] neg_hi:[1,0,0]
	v_pk_fma_f32 v[8:9], v[94:95], v[12:13], v[50:51] op_sel_hi:[1,0,1] neg_lo:[1,0,0] neg_hi:[1,0,0]
	ds_read_b128 v[20:23], v10 offset:4352
	ds_read_b128 v[28:31], v10 offset:4864
	ds_read_b128 v[24:27], v10 offset:4608
	s_waitcnt lgkmcnt(4)
	v_fma_mix_f32 v12, v6, v110, v180 op_sel_hi:[0,1,0]
	v_fma_mix_f32 v12, v7, v110, v12 op_sel:[0,1,0] op_sel_hi:[0,1,0]
	v_fma_mix_f32 v12, v8, v111, v12 op_sel_hi:[0,1,0]
	v_fma_mix_f32 v12, v9, v111, v12 op_sel:[0,1,0] op_sel_hi:[0,1,0]
	v_fma_mix_f32 v54, v6, v90, v180 op_sel_hi:[0,1,0]
	v_fma_mix_f32 v54, v7, v90, v54 op_sel:[0,1,0] op_sel_hi:[0,1,0]
	v_add_f32_dpp v12, v12, v12 row_ror:1 row_mask:0xf bank_mask:0xf bound_ctrl:1
	v_fma_mix_f32 v54, v8, v91, v54 op_sel_hi:[0,1,0]
	v_fma_mix_f32 v54, v9, v91, v54 op_sel:[0,1,0] op_sel_hi:[0,1,0]
	v_add_f32_dpp v12, v12, v12 row_ror:2 row_mask:0xf bank_mask:0xf bound_ctrl:1
	v_pk_fma_f32 v[48:49], v[118:119], v[68:69], v[6:7] op_sel:[0,1,0]
	v_pk_fma_f32 v[50:51], v[120:121], v[68:69], v[8:9] op_sel:[0,1,0]
	v_add_f32_dpp v12, v12, v12 row_ror:4 row_mask:0xf bank_mask:0xf bound_ctrl:1
	s_nop 1
	v_add_f32_dpp v12, v12, v12 row_ror:8 row_mask:0xf bank_mask:0xf bound_ctrl:1
	v_pk_fma_f32 v[6:7], v[114:115], v[12:13], v[48:49] op_sel_hi:[1,0,1] neg_lo:[1,0,0] neg_hi:[1,0,0]
	v_pk_fma_f32 v[8:9], v[116:117], v[12:13], v[50:51] op_sel_hi:[1,0,1] neg_lo:[1,0,0] neg_hi:[1,0,0]
	v_pk_mul_f32 v[6:7], v[6:7], v[106:107]
	v_pk_mul_f32 v[8:9], v[8:9], v[108:109]
	ds_read_b128 v[36:39], v10 offset:5376
	ds_read_b128 v[44:47], v10 offset:5888
	ds_read_b128 v[40:43], v10 offset:5632
	s_waitcnt lgkmcnt(3)
	v_fma_mix_f32 v12, v6, v20, v180 op_sel_hi:[0,1,0]
	v_fma_mix_f32 v12, v7, v20, v12 op_sel:[0,1,0] op_sel_hi:[0,1,0]
	v_fma_mix_f32 v12, v8, v21, v12 op_sel_hi:[0,1,0]
	v_fma_mix_f32 v12, v9, v21, v12 op_sel:[0,1,0] op_sel_hi:[0,1,0]
	v_fma_mix_f32 v55, v6, v112, v180 op_sel_hi:[0,1,0]
	v_fma_mix_f32 v55, v7, v112, v55 op_sel:[0,1,0] op_sel_hi:[0,1,0]
	v_add_f32_dpp v12, v12, v12 row_ror:1 row_mask:0xf bank_mask:0xf bound_ctrl:1
	v_fma_mix_f32 v55, v8, v113, v55 op_sel_hi:[0,1,0]
	v_fma_mix_f32 v55, v9, v113, v55 op_sel:[0,1,0] op_sel_hi:[0,1,0]
	v_add_f32_dpp v12, v12, v12 row_ror:2 row_mask:0xf bank_mask:0xf bound_ctrl:1
	v_pk_fma_f32 v[48:49], v[28:29], v[70:71], v[6:7] op_sel_hi:[1,0,1]
	v_pk_fma_f32 v[50:51], v[30:31], v[70:71], v[8:9] op_sel_hi:[1,0,1]
	v_add_f32_dpp v12, v12, v12 row_ror:4 row_mask:0xf bank_mask:0xf bound_ctrl:1
	s_nop 1
	v_add_f32_dpp v12, v12, v12 row_ror:8 row_mask:0xf bank_mask:0xf bound_ctrl:1
	v_pk_fma_f32 v[6:7], v[24:25], v[12:13], v[48:49] op_sel_hi:[1,0,1] neg_lo:[1,0,0] neg_hi:[1,0,0]
	v_pk_fma_f32 v[8:9], v[26:27], v[12:13], v[50:51] op_sel_hi:[1,0,1] neg_lo:[1,0,0] neg_hi:[1,0,0]
	ds_read_b128 v[88:91], v10 offset:6400
	ds_read_b128 v[96:99], v10 offset:6912
	ds_read_b128 v[92:95], v10 offset:6656
	s_waitcnt lgkmcnt(3)
	v_fma_mix_f32 v12, v6, v36, v180 op_sel_hi:[0,1,0]
	v_fma_mix_f32 v12, v7, v36, v12 op_sel:[0,1,0] op_sel_hi:[0,1,0]
	v_fma_mix_f32 v12, v8, v37, v12 op_sel_hi:[0,1,0]
	v_fma_mix_f32 v12, v9, v37, v12 op_sel:[0,1,0] op_sel_hi:[0,1,0]
	v_fma_mix_f32 v56, v6, v22, v180 op_sel_hi:[0,1,0]
	v_fma_mix_f32 v56, v7, v22, v56 op_sel:[0,1,0] op_sel_hi:[0,1,0]
	v_add_f32_dpp v12, v12, v12 row_ror:1 row_mask:0xf bank_mask:0xf bound_ctrl:1
	v_fma_mix_f32 v56, v8, v23, v56 op_sel_hi:[0,1,0]
	v_fma_mix_f32 v56, v9, v23, v56 op_sel:[0,1,0] op_sel_hi:[0,1,0]
	v_add_f32_dpp v12, v12, v12 row_ror:2 row_mask:0xf bank_mask:0xf bound_ctrl:1
	v_pk_fma_f32 v[48:49], v[44:45], v[70:71], v[6:7] op_sel:[0,1,0]
	v_pk_fma_f32 v[50:51], v[46:47], v[70:71], v[8:9] op_sel:[0,1,0]
	v_add_f32_dpp v12, v12, v12 row_ror:4 row_mask:0xf bank_mask:0xf bound_ctrl:1
	s_nop 1
	v_add_f32_dpp v12, v12, v12 row_ror:8 row_mask:0xf bank_mask:0xf bound_ctrl:1
	v_pk_fma_f32 v[6:7], v[40:41], v[12:13], v[48:49] op_sel_hi:[1,0,1] neg_lo:[1,0,0] neg_hi:[1,0,0]
	v_pk_fma_f32 v[8:9], v[42:43], v[12:13], v[50:51] op_sel_hi:[1,0,1] neg_lo:[1,0,0] neg_hi:[1,0,0]
	ds_read_b128 v[110:113], v10 offset:7424
	ds_read_b128 v[106:109], v10 offset:7168
	ds_read_b128 v[118:121], v10 offset:7936
	ds_read_b128 v[114:117], v10 offset:7680
	ds_read_b128 v[66:69], v11 offset:512
	s_waitcnt lgkmcnt(5)
	v_fma_mix_f32 v12, v6, v88, v180 op_sel_hi:[0,1,0]
	v_fma_mix_f32 v12, v7, v88, v12 op_sel:[0,1,0] op_sel_hi:[0,1,0]
	v_fma_mix_f32 v12, v8, v89, v12 op_sel_hi:[0,1,0]
	v_fma_mix_f32 v12, v9, v89, v12 op_sel:[0,1,0] op_sel_hi:[0,1,0]
	v_fma_mix_f32 v57, v6, v38, v180 op_sel_hi:[0,1,0]
	v_fma_mix_f32 v57, v7, v38, v57 op_sel:[0,1,0] op_sel_hi:[0,1,0]
	v_add_f32_dpp v12, v12, v12 row_ror:1 row_mask:0xf bank_mask:0xf bound_ctrl:1
	v_fma_mix_f32 v57, v8, v39, v57 op_sel_hi:[0,1,0]
	v_fma_mix_f32 v57, v9, v39, v57 op_sel:[0,1,0] op_sel_hi:[0,1,0]
	v_add_f32_dpp v12, v12, v12 row_ror:2 row_mask:0xf bank_mask:0xf bound_ctrl:1
	v_pk_fma_f32 v[48:49], v[96:97], v[72:73], v[6:7] op_sel_hi:[1,0,1]
	v_pk_fma_f32 v[50:51], v[98:99], v[72:73], v[8:9] op_sel_hi:[1,0,1]
	v_add_f32_dpp v12, v12, v12 row_ror:4 row_mask:0xf bank_mask:0xf bound_ctrl:1
	s_nop 1
	v_add_f32_dpp v12, v12, v12 row_ror:8 row_mask:0xf bank_mask:0xf bound_ctrl:1
	v_pk_fma_f32 v[6:7], v[92:93], v[12:13], v[48:49] op_sel_hi:[1,0,1] neg_lo:[1,0,0] neg_hi:[1,0,0]
	v_pk_fma_f32 v[8:9], v[94:95], v[12:13], v[50:51] op_sel_hi:[1,0,1] neg_lo:[1,0,0] neg_hi:[1,0,0]
	ds_read_b128 v[20:23], v10 offset:8448
	ds_read_b128 v[28:31], v10 offset:8960
	ds_read_b128 v[24:27], v10 offset:8704
	s_waitcnt lgkmcnt(4)
	v_fma_mix_f32 v12, v6, v110, v180 op_sel_hi:[0,1,0]
	v_fma_mix_f32 v12, v7, v110, v12 op_sel:[0,1,0] op_sel_hi:[0,1,0]
	v_fma_mix_f32 v12, v8, v111, v12 op_sel_hi:[0,1,0]
	v_fma_mix_f32 v12, v9, v111, v12 op_sel:[0,1,0] op_sel_hi:[0,1,0]
	v_fma_mix_f32 v81, v6, v90, v180 op_sel_hi:[0,1,0]
	v_fma_mix_f32 v81, v7, v90, v81 op_sel:[0,1,0] op_sel_hi:[0,1,0]
	v_add_f32_dpp v12, v12, v12 row_ror:1 row_mask:0xf bank_mask:0xf bound_ctrl:1
	v_fma_mix_f32 v81, v8, v91, v81 op_sel_hi:[0,1,0]
	v_fma_mix_f32 v81, v9, v91, v81 op_sel:[0,1,0] op_sel_hi:[0,1,0]
	v_add_f32_dpp v12, v12, v12 row_ror:2 row_mask:0xf bank_mask:0xf bound_ctrl:1
	v_pk_fma_f32 v[48:49], v[118:119], v[72:73], v[6:7] op_sel:[0,1,0]
	v_pk_fma_f32 v[50:51], v[120:121], v[72:73], v[8:9] op_sel:[0,1,0]
	v_add_f32_dpp v12, v12, v12 row_ror:4 row_mask:0xf bank_mask:0xf bound_ctrl:1
	s_nop 1
	v_add_f32_dpp v12, v12, v12 row_ror:8 row_mask:0xf bank_mask:0xf bound_ctrl:1
	v_pk_fma_f32 v[6:7], v[114:115], v[12:13], v[48:49] op_sel_hi:[1,0,1] neg_lo:[1,0,0] neg_hi:[1,0,0]
	v_pk_fma_f32 v[8:9], v[116:117], v[12:13], v[50:51] op_sel_hi:[1,0,1] neg_lo:[1,0,0] neg_hi:[1,0,0]
	v_pk_mul_f32 v[6:7], v[6:7], v[106:107]
	v_pk_mul_f32 v[8:9], v[8:9], v[108:109]
	ds_read_b128 v[36:39], v10 offset:9472
	ds_read_b128 v[44:47], v10 offset:9984
	ds_read_b128 v[40:43], v10 offset:9728
	s_waitcnt lgkmcnt(3)
	v_fma_mix_f32 v12, v6, v20, v180 op_sel_hi:[0,1,0]
	v_fma_mix_f32 v12, v7, v20, v12 op_sel:[0,1,0] op_sel_hi:[0,1,0]
	v_fma_mix_f32 v12, v8, v21, v12 op_sel_hi:[0,1,0]
	v_fma_mix_f32 v12, v9, v21, v12 op_sel:[0,1,0] op_sel_hi:[0,1,0]
	v_fma_mix_f32 v82, v6, v112, v180 op_sel_hi:[0,1,0]
	v_fma_mix_f32 v82, v7, v112, v82 op_sel:[0,1,0] op_sel_hi:[0,1,0]
	v_add_f32_dpp v12, v12, v12 row_ror:1 row_mask:0xf bank_mask:0xf bound_ctrl:1
	v_fma_mix_f32 v82, v8, v113, v82 op_sel_hi:[0,1,0]
	v_fma_mix_f32 v82, v9, v113, v82 op_sel:[0,1,0] op_sel_hi:[0,1,0]
	v_add_f32_dpp v12, v12, v12 row_ror:2 row_mask:0xf bank_mask:0xf bound_ctrl:1
	v_pk_fma_f32 v[48:49], v[28:29], v[66:67], v[6:7] op_sel_hi:[1,0,1]
	v_pk_fma_f32 v[50:51], v[30:31], v[66:67], v[8:9] op_sel_hi:[1,0,1]
	v_add_f32_dpp v12, v12, v12 row_ror:4 row_mask:0xf bank_mask:0xf bound_ctrl:1
	s_nop 1
	v_add_f32_dpp v12, v12, v12 row_ror:8 row_mask:0xf bank_mask:0xf bound_ctrl:1
	v_pk_fma_f32 v[6:7], v[24:25], v[12:13], v[48:49] op_sel_hi:[1,0,1] neg_lo:[1,0,0] neg_hi:[1,0,0]
	v_pk_fma_f32 v[8:9], v[26:27], v[12:13], v[50:51] op_sel_hi:[1,0,1] neg_lo:[1,0,0] neg_hi:[1,0,0]
	ds_read_b128 v[88:91], v10 offset:10496
	ds_read_b128 v[96:99], v10 offset:11008
	ds_read_b128 v[92:95], v10 offset:10752
	s_waitcnt lgkmcnt(3)
	v_fma_mix_f32 v12, v6, v36, v180 op_sel_hi:[0,1,0]
	v_fma_mix_f32 v12, v7, v36, v12 op_sel:[0,1,0] op_sel_hi:[0,1,0]
	v_fma_mix_f32 v12, v8, v37, v12 op_sel_hi:[0,1,0]
	v_fma_mix_f32 v12, v9, v37, v12 op_sel:[0,1,0] op_sel_hi:[0,1,0]
	v_fma_mix_f32 v83, v6, v22, v180 op_sel_hi:[0,1,0]
	v_fma_mix_f32 v83, v7, v22, v83 op_sel:[0,1,0] op_sel_hi:[0,1,0]
	v_add_f32_dpp v12, v12, v12 row_ror:1 row_mask:0xf bank_mask:0xf bound_ctrl:1
	v_fma_mix_f32 v83, v8, v23, v83 op_sel_hi:[0,1,0]
	v_fma_mix_f32 v83, v9, v23, v83 op_sel:[0,1,0] op_sel_hi:[0,1,0]
	v_add_f32_dpp v12, v12, v12 row_ror:2 row_mask:0xf bank_mask:0xf bound_ctrl:1
	v_pk_fma_f32 v[48:49], v[44:45], v[66:67], v[6:7] op_sel:[0,1,0]
	v_pk_fma_f32 v[50:51], v[46:47], v[66:67], v[8:9] op_sel:[0,1,0]
	v_add_f32_dpp v12, v12, v12 row_ror:4 row_mask:0xf bank_mask:0xf bound_ctrl:1
	s_nop 1
	v_add_f32_dpp v12, v12, v12 row_ror:8 row_mask:0xf bank_mask:0xf bound_ctrl:1
	v_pk_fma_f32 v[6:7], v[40:41], v[12:13], v[48:49] op_sel_hi:[1,0,1] neg_lo:[1,0,0] neg_hi:[1,0,0]
	v_pk_fma_f32 v[8:9], v[42:43], v[12:13], v[50:51] op_sel_hi:[1,0,1] neg_lo:[1,0,0] neg_hi:[1,0,0]
	ds_read_b128 v[110:113], v10 offset:11520
	ds_read_b128 v[106:109], v10 offset:11264
	ds_read_b128 v[118:121], v10 offset:12032
	ds_read_b128 v[114:117], v10 offset:11776
	ds_read_b128 v[70:73], v11 offset:768
	s_waitcnt lgkmcnt(5)
	v_fma_mix_f32 v12, v6, v88, v180 op_sel_hi:[0,1,0]
	v_fma_mix_f32 v12, v7, v88, v12 op_sel:[0,1,0] op_sel_hi:[0,1,0]
	v_fma_mix_f32 v12, v8, v89, v12 op_sel_hi:[0,1,0]
	v_fma_mix_f32 v12, v9, v89, v12 op_sel:[0,1,0] op_sel_hi:[0,1,0]
	v_fma_mix_f32 v100, v6, v38, v180 op_sel_hi:[0,1,0]
	v_fma_mix_f32 v100, v7, v38, v100 op_sel:[0,1,0] op_sel_hi:[0,1,0]
	v_add_f32_dpp v12, v12, v12 row_ror:1 row_mask:0xf bank_mask:0xf bound_ctrl:1
	v_fma_mix_f32 v100, v8, v39, v100 op_sel_hi:[0,1,0]
	v_fma_mix_f32 v100, v9, v39, v100 op_sel:[0,1,0] op_sel_hi:[0,1,0]
	v_add_f32_dpp v12, v12, v12 row_ror:2 row_mask:0xf bank_mask:0xf bound_ctrl:1
	v_pk_fma_f32 v[48:49], v[96:97], v[68:69], v[6:7] op_sel_hi:[1,0,1]
	v_pk_fma_f32 v[50:51], v[98:99], v[68:69], v[8:9] op_sel_hi:[1,0,1]
	v_add_f32_dpp v12, v12, v12 row_ror:4 row_mask:0xf bank_mask:0xf bound_ctrl:1
	s_nop 1
	v_add_f32_dpp v12, v12, v12 row_ror:8 row_mask:0xf bank_mask:0xf bound_ctrl:1
	v_pk_fma_f32 v[6:7], v[92:93], v[12:13], v[48:49] op_sel_hi:[1,0,1] neg_lo:[1,0,0] neg_hi:[1,0,0]
	v_pk_fma_f32 v[8:9], v[94:95], v[12:13], v[50:51] op_sel_hi:[1,0,1] neg_lo:[1,0,0] neg_hi:[1,0,0]
	ds_read_b128 v[20:23], v10 offset:12544
	ds_read_b128 v[28:31], v10 offset:13056
	ds_read_b128 v[24:27], v10 offset:12800
	s_waitcnt lgkmcnt(4)
	v_fma_mix_f32 v12, v6, v110, v180 op_sel_hi:[0,1,0]
	v_fma_mix_f32 v12, v7, v110, v12 op_sel:[0,1,0] op_sel_hi:[0,1,0]
	v_fma_mix_f32 v12, v8, v111, v12 op_sel_hi:[0,1,0]
	v_fma_mix_f32 v12, v9, v111, v12 op_sel:[0,1,0] op_sel_hi:[0,1,0]
	v_fma_mix_f32 v101, v6, v90, v180 op_sel_hi:[0,1,0]
	v_fma_mix_f32 v101, v7, v90, v101 op_sel:[0,1,0] op_sel_hi:[0,1,0]
	v_add_f32_dpp v12, v12, v12 row_ror:1 row_mask:0xf bank_mask:0xf bound_ctrl:1
	v_fma_mix_f32 v101, v8, v91, v101 op_sel_hi:[0,1,0]
	v_fma_mix_f32 v101, v9, v91, v101 op_sel:[0,1,0] op_sel_hi:[0,1,0]
	v_add_f32_dpp v12, v12, v12 row_ror:2 row_mask:0xf bank_mask:0xf bound_ctrl:1
	v_pk_fma_f32 v[48:49], v[118:119], v[68:69], v[6:7] op_sel:[0,1,0]
	v_pk_fma_f32 v[50:51], v[120:121], v[68:69], v[8:9] op_sel:[0,1,0]
	v_add_f32_dpp v12, v12, v12 row_ror:4 row_mask:0xf bank_mask:0xf bound_ctrl:1
	s_nop 1
	v_add_f32_dpp v12, v12, v12 row_ror:8 row_mask:0xf bank_mask:0xf bound_ctrl:1
	v_pk_fma_f32 v[6:7], v[114:115], v[12:13], v[48:49] op_sel_hi:[1,0,1] neg_lo:[1,0,0] neg_hi:[1,0,0]
	v_pk_fma_f32 v[8:9], v[116:117], v[12:13], v[50:51] op_sel_hi:[1,0,1] neg_lo:[1,0,0] neg_hi:[1,0,0]
	v_pk_mul_f32 v[6:7], v[6:7], v[106:107]
	v_pk_mul_f32 v[8:9], v[8:9], v[108:109]
	ds_read_b128 v[36:39], v10 offset:13568
	ds_read_b128 v[44:47], v10 offset:14080
	ds_read_b128 v[40:43], v10 offset:13824
	s_waitcnt lgkmcnt(3)
	v_fma_mix_f32 v12, v6, v20, v180 op_sel_hi:[0,1,0]
	v_fma_mix_f32 v12, v7, v20, v12 op_sel:[0,1,0] op_sel_hi:[0,1,0]
	v_fma_mix_f32 v12, v8, v21, v12 op_sel_hi:[0,1,0]
	v_fma_mix_f32 v12, v9, v21, v12 op_sel:[0,1,0] op_sel_hi:[0,1,0]
	v_fma_mix_f32 v102, v6, v112, v180 op_sel_hi:[0,1,0]
	v_fma_mix_f32 v102, v7, v112, v102 op_sel:[0,1,0] op_sel_hi:[0,1,0]
	v_add_f32_dpp v12, v12, v12 row_ror:1 row_mask:0xf bank_mask:0xf bound_ctrl:1
	v_fma_mix_f32 v102, v8, v113, v102 op_sel_hi:[0,1,0]
	v_fma_mix_f32 v102, v9, v113, v102 op_sel:[0,1,0] op_sel_hi:[0,1,0]
	v_add_f32_dpp v12, v12, v12 row_ror:2 row_mask:0xf bank_mask:0xf bound_ctrl:1
	v_pk_fma_f32 v[48:49], v[28:29], v[70:71], v[6:7] op_sel_hi:[1,0,1]
	v_pk_fma_f32 v[50:51], v[30:31], v[70:71], v[8:9] op_sel_hi:[1,0,1]
	v_add_f32_dpp v12, v12, v12 row_ror:4 row_mask:0xf bank_mask:0xf bound_ctrl:1
	s_nop 1
	v_add_f32_dpp v12, v12, v12 row_ror:8 row_mask:0xf bank_mask:0xf bound_ctrl:1
	v_pk_fma_f32 v[6:7], v[24:25], v[12:13], v[48:49] op_sel_hi:[1,0,1] neg_lo:[1,0,0] neg_hi:[1,0,0]
	v_pk_fma_f32 v[8:9], v[26:27], v[12:13], v[50:51] op_sel_hi:[1,0,1] neg_lo:[1,0,0] neg_hi:[1,0,0]
	ds_read_b128 v[88:91], v10 offset:14592
	ds_read_b128 v[96:99], v10 offset:15104
	ds_read_b128 v[92:95], v10 offset:14848
	s_waitcnt lgkmcnt(3)
	v_fma_mix_f32 v12, v6, v36, v180 op_sel_hi:[0,1,0]
	v_fma_mix_f32 v12, v7, v36, v12 op_sel:[0,1,0] op_sel_hi:[0,1,0]
	v_fma_mix_f32 v12, v8, v37, v12 op_sel_hi:[0,1,0]
	v_fma_mix_f32 v12, v9, v37, v12 op_sel:[0,1,0] op_sel_hi:[0,1,0]
	v_fma_mix_f32 v103, v6, v22, v180 op_sel_hi:[0,1,0]
	v_fma_mix_f32 v103, v7, v22, v103 op_sel:[0,1,0] op_sel_hi:[0,1,0]
	v_add_f32_dpp v12, v12, v12 row_ror:1 row_mask:0xf bank_mask:0xf bound_ctrl:1
	v_fma_mix_f32 v103, v8, v23, v103 op_sel_hi:[0,1,0]
	v_fma_mix_f32 v103, v9, v23, v103 op_sel:[0,1,0] op_sel_hi:[0,1,0]
	v_add_f32_dpp v12, v12, v12 row_ror:2 row_mask:0xf bank_mask:0xf bound_ctrl:1
	v_pk_fma_f32 v[48:49], v[44:45], v[70:71], v[6:7] op_sel:[0,1,0]
	v_pk_fma_f32 v[50:51], v[46:47], v[70:71], v[8:9] op_sel:[0,1,0]
	v_add_f32_dpp v12, v12, v12 row_ror:4 row_mask:0xf bank_mask:0xf bound_ctrl:1
	s_nop 1
	v_add_f32_dpp v12, v12, v12 row_ror:8 row_mask:0xf bank_mask:0xf bound_ctrl:1
	v_pk_fma_f32 v[6:7], v[40:41], v[12:13], v[48:49] op_sel_hi:[1,0,1] neg_lo:[1,0,0] neg_hi:[1,0,0]
	v_pk_fma_f32 v[8:9], v[42:43], v[12:13], v[50:51] op_sel_hi:[1,0,1] neg_lo:[1,0,0] neg_hi:[1,0,0]
	ds_read_b128 v[110:113], v10 offset:15616
	ds_read_b128 v[106:109], v10 offset:15360
	ds_read_b128 v[118:121], v10 offset:16128
	ds_read_b128 v[114:117], v10 offset:15872
	ds_read_b128 v[66:69], v11 offset:1024
	s_waitcnt lgkmcnt(5)
	v_fma_mix_f32 v12, v6, v88, v180 op_sel_hi:[0,1,0]
	v_fma_mix_f32 v12, v7, v88, v12 op_sel:[0,1,0] op_sel_hi:[0,1,0]
	v_fma_mix_f32 v12, v8, v89, v12 op_sel_hi:[0,1,0]
	v_fma_mix_f32 v12, v9, v89, v12 op_sel:[0,1,0] op_sel_hi:[0,1,0]
	v_fma_mix_f32 v104, v6, v38, v180 op_sel_hi:[0,1,0]
	v_fma_mix_f32 v104, v7, v38, v104 op_sel:[0,1,0] op_sel_hi:[0,1,0]
	v_add_f32_dpp v12, v12, v12 row_ror:1 row_mask:0xf bank_mask:0xf bound_ctrl:1
	v_fma_mix_f32 v104, v8, v39, v104 op_sel_hi:[0,1,0]
	v_fma_mix_f32 v104, v9, v39, v104 op_sel:[0,1,0] op_sel_hi:[0,1,0]
	v_add_f32_dpp v12, v12, v12 row_ror:2 row_mask:0xf bank_mask:0xf bound_ctrl:1
	v_pk_fma_f32 v[48:49], v[96:97], v[72:73], v[6:7] op_sel_hi:[1,0,1]
	v_pk_fma_f32 v[50:51], v[98:99], v[72:73], v[8:9] op_sel_hi:[1,0,1]
	v_add_f32_dpp v12, v12, v12 row_ror:4 row_mask:0xf bank_mask:0xf bound_ctrl:1
	s_nop 1
	v_add_f32_dpp v12, v12, v12 row_ror:8 row_mask:0xf bank_mask:0xf bound_ctrl:1
	v_pk_fma_f32 v[6:7], v[92:93], v[12:13], v[48:49] op_sel_hi:[1,0,1] neg_lo:[1,0,0] neg_hi:[1,0,0]
	v_pk_fma_f32 v[8:9], v[94:95], v[12:13], v[50:51] op_sel_hi:[1,0,1] neg_lo:[1,0,0] neg_hi:[1,0,0]
	ds_read_b128 v[20:23], v10 offset:16640
	ds_read_b128 v[28:31], v10 offset:17152
	ds_read_b128 v[24:27], v10 offset:16896
	s_waitcnt lgkmcnt(4)
	v_fma_mix_f32 v12, v6, v110, v180 op_sel_hi:[0,1,0]
	v_fma_mix_f32 v12, v7, v110, v12 op_sel:[0,1,0] op_sel_hi:[0,1,0]
	v_fma_mix_f32 v12, v8, v111, v12 op_sel_hi:[0,1,0]
	v_fma_mix_f32 v12, v9, v111, v12 op_sel:[0,1,0] op_sel_hi:[0,1,0]
	v_fma_mix_f32 v105, v6, v90, v180 op_sel_hi:[0,1,0]
	v_fma_mix_f32 v105, v7, v90, v105 op_sel:[0,1,0] op_sel_hi:[0,1,0]
	v_add_f32_dpp v12, v12, v12 row_ror:1 row_mask:0xf bank_mask:0xf bound_ctrl:1
	v_fma_mix_f32 v105, v8, v91, v105 op_sel_hi:[0,1,0]
	v_fma_mix_f32 v105, v9, v91, v105 op_sel:[0,1,0] op_sel_hi:[0,1,0]
	v_add_f32_dpp v12, v12, v12 row_ror:2 row_mask:0xf bank_mask:0xf bound_ctrl:1
	v_pk_fma_f32 v[48:49], v[118:119], v[72:73], v[6:7] op_sel:[0,1,0]
	v_pk_fma_f32 v[50:51], v[120:121], v[72:73], v[8:9] op_sel:[0,1,0]
	v_add_f32_dpp v12, v12, v12 row_ror:4 row_mask:0xf bank_mask:0xf bound_ctrl:1
	s_nop 1
	v_add_f32_dpp v12, v12, v12 row_ror:8 row_mask:0xf bank_mask:0xf bound_ctrl:1
	v_pk_fma_f32 v[6:7], v[114:115], v[12:13], v[48:49] op_sel_hi:[1,0,1] neg_lo:[1,0,0] neg_hi:[1,0,0]
	v_pk_fma_f32 v[8:9], v[116:117], v[12:13], v[50:51] op_sel_hi:[1,0,1] neg_lo:[1,0,0] neg_hi:[1,0,0]
	v_pk_mul_f32 v[6:7], v[6:7], v[106:107]
	v_pk_mul_f32 v[8:9], v[8:9], v[108:109]
	ds_read_b128 v[36:39], v10 offset:17664
	ds_read_b128 v[44:47], v10 offset:18176
	ds_read_b128 v[40:43], v10 offset:17920
	s_waitcnt lgkmcnt(3)
	v_fma_mix_f32 v12, v6, v20, v180 op_sel_hi:[0,1,0]
	v_fma_mix_f32 v12, v7, v20, v12 op_sel:[0,1,0] op_sel_hi:[0,1,0]
	v_fma_mix_f32 v12, v8, v21, v12 op_sel_hi:[0,1,0]
	v_fma_mix_f32 v12, v9, v21, v12 op_sel:[0,1,0] op_sel_hi:[0,1,0]
	v_fma_mix_f32 v61, v6, v112, v180 op_sel_hi:[0,1,0]
	v_fma_mix_f32 v61, v7, v112, v61 op_sel:[0,1,0] op_sel_hi:[0,1,0]
	v_add_f32_dpp v12, v12, v12 row_ror:1 row_mask:0xf bank_mask:0xf bound_ctrl:1
	v_fma_mix_f32 v61, v8, v113, v61 op_sel_hi:[0,1,0]
	v_fma_mix_f32 v61, v9, v113, v61 op_sel:[0,1,0] op_sel_hi:[0,1,0]
	v_add_f32_dpp v12, v12, v12 row_ror:2 row_mask:0xf bank_mask:0xf bound_ctrl:1
	v_pk_fma_f32 v[48:49], v[28:29], v[66:67], v[6:7] op_sel_hi:[1,0,1]
	v_pk_fma_f32 v[50:51], v[30:31], v[66:67], v[8:9] op_sel_hi:[1,0,1]
	v_add_f32_dpp v12, v12, v12 row_ror:4 row_mask:0xf bank_mask:0xf bound_ctrl:1
	s_nop 1
	v_add_f32_dpp v12, v12, v12 row_ror:8 row_mask:0xf bank_mask:0xf bound_ctrl:1
	v_pk_fma_f32 v[6:7], v[24:25], v[12:13], v[48:49] op_sel_hi:[1,0,1] neg_lo:[1,0,0] neg_hi:[1,0,0]
	v_pk_fma_f32 v[8:9], v[26:27], v[12:13], v[50:51] op_sel_hi:[1,0,1] neg_lo:[1,0,0] neg_hi:[1,0,0]
	ds_read_b128 v[88:91], v10 offset:18688
	ds_read_b128 v[96:99], v10 offset:19200
	ds_read_b128 v[92:95], v10 offset:18944
	s_waitcnt lgkmcnt(3)
	v_fma_mix_f32 v12, v6, v36, v180 op_sel_hi:[0,1,0]
	v_fma_mix_f32 v12, v7, v36, v12 op_sel:[0,1,0] op_sel_hi:[0,1,0]
	v_fma_mix_f32 v12, v8, v37, v12 op_sel_hi:[0,1,0]
	v_fma_mix_f32 v12, v9, v37, v12 op_sel:[0,1,0] op_sel_hi:[0,1,0]
	v_fma_mix_f32 v122, v6, v22, v180 op_sel_hi:[0,1,0]
	v_fma_mix_f32 v122, v7, v22, v122 op_sel:[0,1,0] op_sel_hi:[0,1,0]
	v_add_f32_dpp v12, v12, v12 row_ror:1 row_mask:0xf bank_mask:0xf bound_ctrl:1
	v_fma_mix_f32 v122, v8, v23, v122 op_sel_hi:[0,1,0]
	v_fma_mix_f32 v122, v9, v23, v122 op_sel:[0,1,0] op_sel_hi:[0,1,0]
	v_add_f32_dpp v12, v12, v12 row_ror:2 row_mask:0xf bank_mask:0xf bound_ctrl:1
	v_pk_fma_f32 v[48:49], v[44:45], v[66:67], v[6:7] op_sel:[0,1,0]
	v_pk_fma_f32 v[50:51], v[46:47], v[66:67], v[8:9] op_sel:[0,1,0]
	v_add_f32_dpp v12, v12, v12 row_ror:4 row_mask:0xf bank_mask:0xf bound_ctrl:1
	v_add_f32_dpp v83, v83, v83 row_ror:8 row_mask:0xf bank_mask:0xc
	v_add_f32_dpp v83, v52, v52 row_ror:8 row_mask:0xf bank_mask:0x3
	v_add_f32_dpp v100, v100, v100 row_ror:8 row_mask:0xf bank_mask:0xc
	v_add_f32_dpp v12, v12, v12 row_ror:8 row_mask:0xf bank_mask:0xf bound_ctrl:1
	v_pk_fma_f32 v[6:7], v[40:41], v[12:13], v[48:49] op_sel_hi:[1,0,1] neg_lo:[1,0,0] neg_hi:[1,0,0]
	v_pk_fma_f32 v[8:9], v[42:43], v[12:13], v[50:51] op_sel_hi:[1,0,1] neg_lo:[1,0,0] neg_hi:[1,0,0]
	ds_read_b128 v[110:113], v10 offset:19712
	ds_read_b128 v[106:109], v10 offset:19456
	ds_read_b128 v[118:121], v10 offset:20224
	ds_read_b128 v[114:117], v10 offset:19968
	ds_read_b128 v[70:73], v11 offset:1280
	s_waitcnt lgkmcnt(5)
	v_fma_mix_f32 v12, v6, v88, v180 op_sel_hi:[0,1,0]
	v_fma_mix_f32 v12, v7, v88, v12 op_sel:[0,1,0] op_sel_hi:[0,1,0]
	v_fma_mix_f32 v12, v8, v89, v12 op_sel_hi:[0,1,0]
	v_fma_mix_f32 v12, v9, v89, v12 op_sel:[0,1,0] op_sel_hi:[0,1,0]
	v_fma_mix_f32 v123, v6, v38, v180 op_sel_hi:[0,1,0]
	v_fma_mix_f32 v123, v7, v38, v123 op_sel:[0,1,0] op_sel_hi:[0,1,0]
	v_add_f32_dpp v12, v12, v12 row_ror:1 row_mask:0xf bank_mask:0xf bound_ctrl:1
	v_fma_mix_f32 v123, v8, v39, v123 op_sel_hi:[0,1,0]
	v_fma_mix_f32 v123, v9, v39, v123 op_sel:[0,1,0] op_sel_hi:[0,1,0]
	v_add_f32_dpp v12, v12, v12 row_ror:2 row_mask:0xf bank_mask:0xf bound_ctrl:1
	v_pk_fma_f32 v[48:49], v[96:97], v[68:69], v[6:7] op_sel_hi:[1,0,1]
	v_pk_fma_f32 v[50:51], v[98:99], v[68:69], v[8:9] op_sel_hi:[1,0,1]
	v_add_f32_dpp v12, v12, v12 row_ror:4 row_mask:0xf bank_mask:0xf bound_ctrl:1
	v_add_f32_dpp v100, v53, v53 row_ror:8 row_mask:0xf bank_mask:0x3
	v_add_f32_dpp v101, v101, v101 row_ror:8 row_mask:0xf bank_mask:0xc
	v_add_f32_dpp v101, v54, v54 row_ror:8 row_mask:0xf bank_mask:0x3
	v_add_f32_dpp v12, v12, v12 row_ror:8 row_mask:0xf bank_mask:0xf bound_ctrl:1
	v_pk_fma_f32 v[6:7], v[92:93], v[12:13], v[48:49] op_sel_hi:[1,0,1] neg_lo:[1,0,0] neg_hi:[1,0,0]
	v_pk_fma_f32 v[8:9], v[94:95], v[12:13], v[50:51] op_sel_hi:[1,0,1] neg_lo:[1,0,0] neg_hi:[1,0,0]
	ds_read_b128 v[20:23], v10 offset:20736
	ds_read_b128 v[28:31], v10 offset:21248
	ds_read_b128 v[24:27], v10 offset:20992
	s_waitcnt lgkmcnt(4)
	v_fma_mix_f32 v12, v6, v110, v180 op_sel_hi:[0,1,0]
	v_fma_mix_f32 v12, v7, v110, v12 op_sel:[0,1,0] op_sel_hi:[0,1,0]
	v_fma_mix_f32 v12, v8, v111, v12 op_sel_hi:[0,1,0]
	v_fma_mix_f32 v12, v9, v111, v12 op_sel:[0,1,0] op_sel_hi:[0,1,0]
	v_fma_mix_f32 v124, v6, v90, v180 op_sel_hi:[0,1,0]
	v_fma_mix_f32 v124, v7, v90, v124 op_sel:[0,1,0] op_sel_hi:[0,1,0]
	v_add_f32_dpp v12, v12, v12 row_ror:1 row_mask:0xf bank_mask:0xf bound_ctrl:1
	v_fma_mix_f32 v124, v8, v91, v124 op_sel_hi:[0,1,0]
	v_fma_mix_f32 v124, v9, v91, v124 op_sel:[0,1,0] op_sel_hi:[0,1,0]
	v_add_f32_dpp v12, v12, v12 row_ror:2 row_mask:0xf bank_mask:0xf bound_ctrl:1
	v_pk_fma_f32 v[48:49], v[118:119], v[68:69], v[6:7] op_sel:[0,1,0]
	v_pk_fma_f32 v[50:51], v[120:121], v[68:69], v[8:9] op_sel:[0,1,0]
	v_add_f32_dpp v12, v12, v12 row_ror:4 row_mask:0xf bank_mask:0xf bound_ctrl:1
	v_add_f32_dpp v102, v102, v102 row_ror:8 row_mask:0xf bank_mask:0xc
	v_add_f32_dpp v102, v55, v55 row_ror:8 row_mask:0xf bank_mask:0x3
	v_add_f32_dpp v103, v103, v103 row_ror:8 row_mask:0xf bank_mask:0xc
	v_add_f32_dpp v12, v12, v12 row_ror:8 row_mask:0xf bank_mask:0xf bound_ctrl:1
	v_pk_fma_f32 v[6:7], v[114:115], v[12:13], v[48:49] op_sel_hi:[1,0,1] neg_lo:[1,0,0] neg_hi:[1,0,0]
	v_pk_fma_f32 v[8:9], v[116:117], v[12:13], v[50:51] op_sel_hi:[1,0,1] neg_lo:[1,0,0] neg_hi:[1,0,0]
	v_pk_mul_f32 v[6:7], v[6:7], v[106:107]
	v_pk_mul_f32 v[8:9], v[8:9], v[108:109]
	ds_read_b128 v[36:39], v10 offset:21760
	ds_read_b128 v[44:47], v10 offset:22272
	ds_read_b128 v[40:43], v10 offset:22016
	s_waitcnt lgkmcnt(3)
	v_fma_mix_f32 v12, v6, v20, v180 op_sel_hi:[0,1,0]
	v_fma_mix_f32 v12, v7, v20, v12 op_sel:[0,1,0] op_sel_hi:[0,1,0]
	v_fma_mix_f32 v12, v8, v21, v12 op_sel_hi:[0,1,0]
	v_fma_mix_f32 v12, v9, v21, v12 op_sel:[0,1,0] op_sel_hi:[0,1,0]
	v_fma_mix_f32 v125, v6, v112, v180 op_sel_hi:[0,1,0]
	v_fma_mix_f32 v125, v7, v112, v125 op_sel:[0,1,0] op_sel_hi:[0,1,0]
	v_add_f32_dpp v12, v12, v12 row_ror:1 row_mask:0xf bank_mask:0xf bound_ctrl:1
	v_fma_mix_f32 v125, v8, v113, v125 op_sel_hi:[0,1,0]
	v_fma_mix_f32 v125, v9, v113, v125 op_sel:[0,1,0] op_sel_hi:[0,1,0]
	v_add_f32_dpp v12, v12, v12 row_ror:2 row_mask:0xf bank_mask:0xf bound_ctrl:1
	v_pk_fma_f32 v[48:49], v[28:29], v[70:71], v[6:7] op_sel_hi:[1,0,1]
	v_pk_fma_f32 v[50:51], v[30:31], v[70:71], v[8:9] op_sel_hi:[1,0,1]
	v_add_f32_dpp v12, v12, v12 row_ror:4 row_mask:0xf bank_mask:0xf bound_ctrl:1
	v_add_f32_dpp v103, v56, v56 row_ror:8 row_mask:0xf bank_mask:0x3
	v_add_f32_dpp v104, v104, v104 row_ror:8 row_mask:0xf bank_mask:0xc
	v_add_f32_dpp v104, v57, v57 row_ror:8 row_mask:0xf bank_mask:0x3
	v_add_f32_dpp v12, v12, v12 row_ror:8 row_mask:0xf bank_mask:0xf bound_ctrl:1
	v_pk_fma_f32 v[6:7], v[24:25], v[12:13], v[48:49] op_sel_hi:[1,0,1] neg_lo:[1,0,0] neg_hi:[1,0,0]
	v_pk_fma_f32 v[8:9], v[26:27], v[12:13], v[50:51] op_sel_hi:[1,0,1] neg_lo:[1,0,0] neg_hi:[1,0,0]
	ds_read_b128 v[88:91], v10 offset:22784
	ds_read_b128 v[96:99], v10 offset:23296
	ds_read_b128 v[92:95], v10 offset:23040
	s_waitcnt lgkmcnt(3)
	v_fma_mix_f32 v12, v6, v36, v180 op_sel_hi:[0,1,0]
	v_fma_mix_f32 v12, v7, v36, v12 op_sel:[0,1,0] op_sel_hi:[0,1,0]
	v_fma_mix_f32 v12, v8, v37, v12 op_sel_hi:[0,1,0]
	v_fma_mix_f32 v12, v9, v37, v12 op_sel:[0,1,0] op_sel_hi:[0,1,0]
	v_fma_mix_f32 v126, v6, v22, v180 op_sel_hi:[0,1,0]
	v_fma_mix_f32 v126, v7, v22, v126 op_sel:[0,1,0] op_sel_hi:[0,1,0]
	v_add_f32_dpp v12, v12, v12 row_ror:1 row_mask:0xf bank_mask:0xf bound_ctrl:1
	v_fma_mix_f32 v126, v8, v23, v126 op_sel_hi:[0,1,0]
	v_fma_mix_f32 v126, v9, v23, v126 op_sel:[0,1,0] op_sel_hi:[0,1,0]
	v_add_f32_dpp v12, v12, v12 row_ror:2 row_mask:0xf bank_mask:0xf bound_ctrl:1
	v_pk_fma_f32 v[48:49], v[44:45], v[70:71], v[6:7] op_sel:[0,1,0]
	v_pk_fma_f32 v[50:51], v[46:47], v[70:71], v[8:9] op_sel:[0,1,0]
	v_add_f32_dpp v12, v12, v12 row_ror:4 row_mask:0xf bank_mask:0xf bound_ctrl:1
	v_add_f32_dpp v105, v105, v105 row_ror:8 row_mask:0xf bank_mask:0xc
	v_add_f32_dpp v105, v81, v81 row_ror:8 row_mask:0xf bank_mask:0x3
	v_add_f32_dpp v12, v12, v12 row_ror:8 row_mask:0xf bank_mask:0xf bound_ctrl:1
	v_pk_fma_f32 v[6:7], v[40:41], v[12:13], v[48:49] op_sel_hi:[1,0,1] neg_lo:[1,0,0] neg_hi:[1,0,0]
	v_pk_fma_f32 v[8:9], v[42:43], v[12:13], v[50:51] op_sel_hi:[1,0,1] neg_lo:[1,0,0] neg_hi:[1,0,0]
	ds_read_b128 v[110:113], v10 offset:23808
	ds_read_b128 v[106:109], v10 offset:23552
	ds_read_b128 v[118:121], v10 offset:24320
	ds_read_b128 v[114:117], v10 offset:24064
	ds_read_b128 v[66:69], v11 offset:1536
	s_waitcnt lgkmcnt(5)
	v_fma_mix_f32 v12, v6, v88, v180 op_sel_hi:[0,1,0]
	v_fma_mix_f32 v12, v7, v88, v12 op_sel:[0,1,0] op_sel_hi:[0,1,0]
	v_fma_mix_f32 v12, v8, v89, v12 op_sel_hi:[0,1,0]
	v_fma_mix_f32 v12, v9, v89, v12 op_sel:[0,1,0] op_sel_hi:[0,1,0]
	v_fma_mix_f32 v127, v6, v38, v180 op_sel_hi:[0,1,0]
	v_fma_mix_f32 v127, v7, v38, v127 op_sel:[0,1,0] op_sel_hi:[0,1,0]
	v_add_f32_dpp v12, v12, v12 row_ror:1 row_mask:0xf bank_mask:0xf bound_ctrl:1
	v_fma_mix_f32 v127, v8, v39, v127 op_sel_hi:[0,1,0]
	v_fma_mix_f32 v127, v9, v39, v127 op_sel:[0,1,0] op_sel_hi:[0,1,0]
	v_add_f32_dpp v12, v12, v12 row_ror:2 row_mask:0xf bank_mask:0xf bound_ctrl:1
	v_pk_fma_f32 v[48:49], v[96:97], v[72:73], v[6:7] op_sel_hi:[1,0,1]
	v_pk_fma_f32 v[50:51], v[98:99], v[72:73], v[8:9] op_sel_hi:[1,0,1]
	v_add_f32_dpp v12, v12, v12 row_ror:4 row_mask:0xf bank_mask:0xf bound_ctrl:1
	v_add_f32_dpp v61, v61, v61 row_ror:8 row_mask:0xf bank_mask:0xc
	v_add_f32_dpp v61, v82, v82 row_ror:8 row_mask:0xf bank_mask:0x3
	v_add_f32_dpp v12, v12, v12 row_ror:8 row_mask:0xf bank_mask:0xf bound_ctrl:1
	v_pk_fma_f32 v[6:7], v[92:93], v[12:13], v[48:49] op_sel_hi:[1,0,1] neg_lo:[1,0,0] neg_hi:[1,0,0]
	v_pk_fma_f32 v[8:9], v[94:95], v[12:13], v[50:51] op_sel_hi:[1,0,1] neg_lo:[1,0,0] neg_hi:[1,0,0]
	ds_read_b128 v[20:23], v10 offset:24832
	ds_read_b128 v[28:31], v10 offset:25344
	ds_read_b128 v[24:27], v10 offset:25088
	s_waitcnt lgkmcnt(4)
	v_fma_mix_f32 v12, v6, v110, v180 op_sel_hi:[0,1,0]
	v_fma_mix_f32 v12, v7, v110, v12 op_sel:[0,1,0] op_sel_hi:[0,1,0]
	v_fma_mix_f32 v12, v8, v111, v12 op_sel_hi:[0,1,0]
	v_fma_mix_f32 v12, v9, v111, v12 op_sel:[0,1,0] op_sel_hi:[0,1,0]
	v_fma_mix_f32 v128, v6, v90, v180 op_sel_hi:[0,1,0]
	v_fma_mix_f32 v128, v7, v90, v128 op_sel:[0,1,0] op_sel_hi:[0,1,0]
	v_add_f32_dpp v12, v12, v12 row_ror:1 row_mask:0xf bank_mask:0xf bound_ctrl:1
	v_fma_mix_f32 v128, v8, v91, v128 op_sel_hi:[0,1,0]
	v_fma_mix_f32 v128, v9, v91, v128 op_sel:[0,1,0] op_sel_hi:[0,1,0]
	v_add_f32_dpp v12, v12, v12 row_ror:2 row_mask:0xf bank_mask:0xf bound_ctrl:1
	v_pk_fma_f32 v[48:49], v[118:119], v[72:73], v[6:7] op_sel:[0,1,0]
	v_pk_fma_f32 v[50:51], v[120:121], v[72:73], v[8:9] op_sel:[0,1,0]
	v_add_f32_dpp v12, v12, v12 row_ror:4 row_mask:0xf bank_mask:0xf bound_ctrl:1
	v_add_f32_dpp v103, v103, v103 row_ror:4 row_mask:0xf bank_mask:0xa
	v_add_f32_dpp v103, v83, v83 row_ror:12 row_mask:0xf bank_mask:0x5
	v_add_f32_dpp v104, v104, v104 row_ror:4 row_mask:0xf bank_mask:0xa
	v_add_f32_dpp v12, v12, v12 row_ror:8 row_mask:0xf bank_mask:0xf bound_ctrl:1
	v_pk_fma_f32 v[6:7], v[114:115], v[12:13], v[48:49] op_sel_hi:[1,0,1] neg_lo:[1,0,0] neg_hi:[1,0,0]
	v_pk_fma_f32 v[8:9], v[116:117], v[12:13], v[50:51] op_sel_hi:[1,0,1] neg_lo:[1,0,0] neg_hi:[1,0,0]
	v_pk_mul_f32 v[6:7], v[6:7], v[106:107]
	v_pk_mul_f32 v[8:9], v[8:9], v[108:109]
	ds_read_b128 v[36:39], v10 offset:25856
	ds_read_b128 v[44:47], v10 offset:26368
	ds_read_b128 v[40:43], v10 offset:26112
	s_waitcnt lgkmcnt(3)
	v_fma_mix_f32 v12, v6, v20, v180 op_sel_hi:[0,1,0]
	v_fma_mix_f32 v12, v7, v20, v12 op_sel:[0,1,0] op_sel_hi:[0,1,0]
	v_fma_mix_f32 v12, v8, v21, v12 op_sel_hi:[0,1,0]
	v_fma_mix_f32 v12, v9, v21, v12 op_sel:[0,1,0] op_sel_hi:[0,1,0]
	v_fma_mix_f32 v129, v6, v112, v180 op_sel_hi:[0,1,0]
	v_fma_mix_f32 v129, v7, v112, v129 op_sel:[0,1,0] op_sel_hi:[0,1,0]
	v_add_f32_dpp v12, v12, v12 row_ror:1 row_mask:0xf bank_mask:0xf bound_ctrl:1
	v_fma_mix_f32 v129, v8, v113, v129 op_sel_hi:[0,1,0]
	v_fma_mix_f32 v129, v9, v113, v129 op_sel:[0,1,0] op_sel_hi:[0,1,0]
	v_add_f32_dpp v12, v12, v12 row_ror:2 row_mask:0xf bank_mask:0xf bound_ctrl:1
	v_pk_fma_f32 v[48:49], v[28:29], v[66:67], v[6:7] op_sel_hi:[1,0,1]
	v_pk_fma_f32 v[50:51], v[30:31], v[66:67], v[8:9] op_sel_hi:[1,0,1]
	v_add_f32_dpp v12, v12, v12 row_ror:4 row_mask:0xf bank_mask:0xf bound_ctrl:1
	v_add_f32_dpp v104, v100, v100 row_ror:12 row_mask:0xf bank_mask:0x5
	v_add_f32_dpp v105, v105, v105 row_ror:4 row_mask:0xf bank_mask:0xa
	v_add_f32_dpp v105, v101, v101 row_ror:12 row_mask:0xf bank_mask:0x5
	v_add_f32_dpp v12, v12, v12 row_ror:8 row_mask:0xf bank_mask:0xf bound_ctrl:1
	v_pk_fma_f32 v[6:7], v[24:25], v[12:13], v[48:49] op_sel_hi:[1,0,1] neg_lo:[1,0,0] neg_hi:[1,0,0]
	v_pk_fma_f32 v[8:9], v[26:27], v[12:13], v[50:51] op_sel_hi:[1,0,1] neg_lo:[1,0,0] neg_hi:[1,0,0]
	ds_read_b128 v[88:91], v10 offset:26880
	ds_read_b128 v[96:99], v10 offset:27392
	ds_read_b128 v[92:95], v10 offset:27136
	s_waitcnt lgkmcnt(3)
	v_fma_mix_f32 v12, v6, v36, v180 op_sel_hi:[0,1,0]
	v_fma_mix_f32 v12, v7, v36, v12 op_sel:[0,1,0] op_sel_hi:[0,1,0]
	v_fma_mix_f32 v12, v8, v37, v12 op_sel_hi:[0,1,0]
	v_fma_mix_f32 v12, v9, v37, v12 op_sel:[0,1,0] op_sel_hi:[0,1,0]
	v_fma_mix_f32 v130, v6, v22, v180 op_sel_hi:[0,1,0]
	v_fma_mix_f32 v130, v7, v22, v130 op_sel:[0,1,0] op_sel_hi:[0,1,0]
	v_add_f32_dpp v12, v12, v12 row_ror:1 row_mask:0xf bank_mask:0xf bound_ctrl:1
	v_fma_mix_f32 v130, v8, v23, v130 op_sel_hi:[0,1,0]
	v_fma_mix_f32 v130, v9, v23, v130 op_sel:[0,1,0] op_sel_hi:[0,1,0]
	v_add_f32_dpp v12, v12, v12 row_ror:2 row_mask:0xf bank_mask:0xf bound_ctrl:1
	v_pk_fma_f32 v[48:49], v[44:45], v[66:67], v[6:7] op_sel:[0,1,0]
	v_pk_fma_f32 v[50:51], v[46:47], v[66:67], v[8:9] op_sel:[0,1,0]
	v_add_f32_dpp v12, v12, v12 row_ror:4 row_mask:0xf bank_mask:0xf bound_ctrl:1
	v_add_f32_dpp v61, v61, v61 row_ror:4 row_mask:0xf bank_mask:0xa
	v_add_f32_dpp v61, v102, v102 row_ror:12 row_mask:0xf bank_mask:0x5
	v_add_f32_dpp v12, v12, v12 row_ror:8 row_mask:0xf bank_mask:0xf bound_ctrl:1
	v_pk_fma_f32 v[6:7], v[40:41], v[12:13], v[48:49] op_sel_hi:[1,0,1] neg_lo:[1,0,0] neg_hi:[1,0,0]
	v_pk_fma_f32 v[8:9], v[42:43], v[12:13], v[50:51] op_sel_hi:[1,0,1] neg_lo:[1,0,0] neg_hi:[1,0,0]
	ds_read_b128 v[110:113], v10 offset:27904
	ds_read_b128 v[106:109], v10 offset:27648
	ds_read_b128 v[118:121], v10 offset:28416
	ds_read_b128 v[114:117], v10 offset:28160
	ds_read_b128 v[70:73], v11 offset:1792
	s_waitcnt lgkmcnt(5)
	v_fma_mix_f32 v12, v6, v88, v180 op_sel_hi:[0,1,0]
	v_fma_mix_f32 v12, v7, v88, v12 op_sel:[0,1,0] op_sel_hi:[0,1,0]
	v_fma_mix_f32 v12, v8, v89, v12 op_sel_hi:[0,1,0]
	v_fma_mix_f32 v12, v9, v89, v12 op_sel:[0,1,0] op_sel_hi:[0,1,0]
	v_fma_mix_f32 v131, v6, v38, v180 op_sel_hi:[0,1,0]
	v_fma_mix_f32 v131, v7, v38, v131 op_sel:[0,1,0] op_sel_hi:[0,1,0]
	v_add_f32_dpp v12, v12, v12 row_ror:1 row_mask:0xf bank_mask:0xf bound_ctrl:1
	v_fma_mix_f32 v131, v8, v39, v131 op_sel_hi:[0,1,0]
	v_fma_mix_f32 v131, v9, v39, v131 op_sel:[0,1,0] op_sel_hi:[0,1,0]
	v_add_f32_dpp v12, v12, v12 row_ror:2 row_mask:0xf bank_mask:0xf bound_ctrl:1
	v_pk_fma_f32 v[48:49], v[96:97], v[68:69], v[6:7] op_sel_hi:[1,0,1]
	v_pk_fma_f32 v[50:51], v[98:99], v[68:69], v[8:9] op_sel_hi:[1,0,1]
	v_add_f32_dpp v12, v12, v12 row_ror:4 row_mask:0xf bank_mask:0xf bound_ctrl:1
	v_cndmask_b32_e64 v62, v105, v103, s[38:39]
	v_cndmask_b32_e64 v63, v103, v105, s[38:39]
	v_add_f32_dpp v12, v12, v12 row_ror:8 row_mask:0xf bank_mask:0xf bound_ctrl:1
	v_pk_fma_f32 v[6:7], v[92:93], v[12:13], v[48:49] op_sel_hi:[1,0,1] neg_lo:[1,0,0] neg_hi:[1,0,0]
	v_pk_fma_f32 v[8:9], v[94:95], v[12:13], v[50:51] op_sel_hi:[1,0,1] neg_lo:[1,0,0] neg_hi:[1,0,0]
	ds_read_b128 v[20:23], v10 offset:28928
	ds_read_b128 v[28:31], v10 offset:29440
	ds_read_b128 v[24:27], v10 offset:29184
	s_waitcnt lgkmcnt(4)
	v_fma_mix_f32 v12, v6, v110, v180 op_sel_hi:[0,1,0]
	v_fma_mix_f32 v12, v7, v110, v12 op_sel:[0,1,0] op_sel_hi:[0,1,0]
	v_fma_mix_f32 v12, v8, v111, v12 op_sel_hi:[0,1,0]
	v_fma_mix_f32 v12, v9, v111, v12 op_sel:[0,1,0] op_sel_hi:[0,1,0]
	v_fma_mix_f32 v132, v6, v90, v180 op_sel_hi:[0,1,0]
	v_fma_mix_f32 v132, v7, v90, v132 op_sel:[0,1,0] op_sel_hi:[0,1,0]
	v_add_f32_dpp v12, v12, v12 row_ror:1 row_mask:0xf bank_mask:0xf bound_ctrl:1
	v_fma_mix_f32 v132, v8, v91, v132 op_sel_hi:[0,1,0]
	v_fma_mix_f32 v132, v9, v91, v132 op_sel:[0,1,0] op_sel_hi:[0,1,0]
	v_add_f32_dpp v12, v12, v12 row_ror:2 row_mask:0xf bank_mask:0xf bound_ctrl:1
	v_pk_fma_f32 v[48:49], v[118:119], v[68:69], v[6:7] op_sel:[0,1,0]
	v_pk_fma_f32 v[50:51], v[120:121], v[68:69], v[8:9] op_sel:[0,1,0]
	v_add_f32_dpp v12, v12, v12 row_ror:4 row_mask:0xf bank_mask:0xf bound_ctrl:1
	v_cndmask_b32_e64 v64, v61, v104, s[38:39]
	v_cndmask_b32_e64 v65, v104, v61, s[38:39]
	v_add_f32_dpp v12, v12, v12 row_ror:8 row_mask:0xf bank_mask:0xf bound_ctrl:1
	v_pk_fma_f32 v[6:7], v[114:115], v[12:13], v[48:49] op_sel_hi:[1,0,1] neg_lo:[1,0,0] neg_hi:[1,0,0]
	v_pk_fma_f32 v[8:9], v[116:117], v[12:13], v[50:51] op_sel_hi:[1,0,1] neg_lo:[1,0,0] neg_hi:[1,0,0]
	v_pk_mul_f32 v[6:7], v[6:7], v[106:107]
	v_pk_mul_f32 v[8:9], v[8:9], v[108:109]
	ds_read_b128 v[36:39], v10 offset:29952
	ds_read_b128 v[44:47], v10 offset:30464
	ds_read_b128 v[40:43], v10 offset:30208
	s_waitcnt lgkmcnt(3)
	v_fma_mix_f32 v12, v6, v20, v180 op_sel_hi:[0,1,0]
	v_fma_mix_f32 v12, v7, v20, v12 op_sel:[0,1,0] op_sel_hi:[0,1,0]
	v_fma_mix_f32 v12, v8, v21, v12 op_sel_hi:[0,1,0]
	v_fma_mix_f32 v12, v9, v21, v12 op_sel:[0,1,0] op_sel_hi:[0,1,0]
	v_fma_mix_f32 v133, v6, v112, v180 op_sel_hi:[0,1,0]
	v_fma_mix_f32 v133, v7, v112, v133 op_sel:[0,1,0] op_sel_hi:[0,1,0]
	v_add_f32_dpp v12, v12, v12 row_ror:1 row_mask:0xf bank_mask:0xf bound_ctrl:1
	v_fma_mix_f32 v133, v8, v113, v133 op_sel_hi:[0,1,0]
	v_fma_mix_f32 v133, v9, v113, v133 op_sel:[0,1,0] op_sel_hi:[0,1,0]
	v_add_f32_dpp v12, v12, v12 row_ror:2 row_mask:0xf bank_mask:0xf bound_ctrl:1
	v_pk_fma_f32 v[48:49], v[28:29], v[70:71], v[6:7] op_sel_hi:[1,0,1]
	v_pk_fma_f32 v[50:51], v[30:31], v[70:71], v[8:9] op_sel_hi:[1,0,1]
	v_add_f32_dpp v12, v12, v12 row_ror:4 row_mask:0xf bank_mask:0xf bound_ctrl:1
	v_add_f32_dpp v62, v63, v62 quad_perm:[2,3,0,1] row_mask:0xf bank_mask:0xf bound_ctrl:1
	v_add_f32_dpp v63, v65, v64 quad_perm:[2,3,0,1] row_mask:0xf bank_mask:0xf bound_ctrl:1
	v_add_f32_dpp v12, v12, v12 row_ror:8 row_mask:0xf bank_mask:0xf bound_ctrl:1
	v_pk_fma_f32 v[6:7], v[24:25], v[12:13], v[48:49] op_sel_hi:[1,0,1] neg_lo:[1,0,0] neg_hi:[1,0,0]
	v_pk_fma_f32 v[8:9], v[26:27], v[12:13], v[50:51] op_sel_hi:[1,0,1] neg_lo:[1,0,0] neg_hi:[1,0,0]
	ds_read_b128 v[88:91], v10 offset:30976
	ds_read_b128 v[96:99], v10 offset:31488
	ds_read_b128 v[92:95], v10 offset:31232
	s_waitcnt lgkmcnt(3)
	v_fma_mix_f32 v12, v6, v36, v180 op_sel_hi:[0,1,0]
	v_fma_mix_f32 v12, v7, v36, v12 op_sel:[0,1,0] op_sel_hi:[0,1,0]
	v_fma_mix_f32 v12, v8, v37, v12 op_sel_hi:[0,1,0]
	v_fma_mix_f32 v12, v9, v37, v12 op_sel:[0,1,0] op_sel_hi:[0,1,0]
	v_fma_mix_f32 v134, v6, v22, v180 op_sel_hi:[0,1,0]
	v_fma_mix_f32 v134, v7, v22, v134 op_sel:[0,1,0] op_sel_hi:[0,1,0]
	v_add_f32_dpp v12, v12, v12 row_ror:1 row_mask:0xf bank_mask:0xf bound_ctrl:1
	v_fma_mix_f32 v134, v8, v23, v134 op_sel_hi:[0,1,0]
	v_fma_mix_f32 v134, v9, v23, v134 op_sel:[0,1,0] op_sel_hi:[0,1,0]
	v_add_f32_dpp v12, v12, v12 row_ror:2 row_mask:0xf bank_mask:0xf bound_ctrl:1
	v_pk_fma_f32 v[48:49], v[44:45], v[70:71], v[6:7] op_sel:[0,1,0]
	v_pk_fma_f32 v[50:51], v[46:47], v[70:71], v[8:9] op_sel:[0,1,0]
	v_add_f32_dpp v12, v12, v12 row_ror:4 row_mask:0xf bank_mask:0xf bound_ctrl:1
	v_cndmask_b32_e64 v65, v63, v62, s[40:41]
	v_cndmask_b32_e64 v62, v62, v63, s[40:41]
	v_add_f32_dpp v12, v12, v12 row_ror:8 row_mask:0xf bank_mask:0xf bound_ctrl:1
	v_pk_fma_f32 v[6:7], v[40:41], v[12:13], v[48:49] op_sel_hi:[1,0,1] neg_lo:[1,0,0] neg_hi:[1,0,0]
	v_pk_fma_f32 v[8:9], v[42:43], v[12:13], v[50:51] op_sel_hi:[1,0,1] neg_lo:[1,0,0] neg_hi:[1,0,0]
	ds_read_b128 v[110:113], v10 offset:32000
	ds_read_b128 v[106:109], v10 offset:31744
	ds_read_b128 v[118:121], v10 offset:32512
	ds_read_b128 v[114:117], v10 offset:32256
	ds_read_b128 v[66:69], v11 offset:2048
	s_waitcnt lgkmcnt(5)
	v_fma_mix_f32 v12, v6, v88, v180 op_sel_hi:[0,1,0]
	v_fma_mix_f32 v12, v7, v88, v12 op_sel:[0,1,0] op_sel_hi:[0,1,0]
	v_fma_mix_f32 v12, v8, v89, v12 op_sel_hi:[0,1,0]
	v_fma_mix_f32 v12, v9, v89, v12 op_sel:[0,1,0] op_sel_hi:[0,1,0]
	v_fma_mix_f32 v135, v6, v38, v180 op_sel_hi:[0,1,0]
	v_fma_mix_f32 v135, v7, v38, v135 op_sel:[0,1,0] op_sel_hi:[0,1,0]
	v_add_f32_dpp v12, v12, v12 row_ror:1 row_mask:0xf bank_mask:0xf bound_ctrl:1
	v_fma_mix_f32 v135, v8, v39, v135 op_sel_hi:[0,1,0]
	v_fma_mix_f32 v135, v9, v39, v135 op_sel:[0,1,0] op_sel_hi:[0,1,0]
	v_add_f32_dpp v12, v12, v12 row_ror:2 row_mask:0xf bank_mask:0xf bound_ctrl:1
	v_pk_fma_f32 v[48:49], v[96:97], v[72:73], v[6:7] op_sel_hi:[1,0,1]
	v_pk_fma_f32 v[50:51], v[98:99], v[72:73], v[8:9] op_sel_hi:[1,0,1]
	v_add_f32_dpp v12, v12, v12 row_ror:4 row_mask:0xf bank_mask:0xf bound_ctrl:1
	v_add_f32_dpp v62, v62, v65 quad_perm:[1,0,3,2] row_mask:0xf bank_mask:0xf bound_ctrl:1
	v_cvt_pk_bf16_f32 v62, v62, v62
	v_add_f32_dpp v12, v12, v12 row_ror:8 row_mask:0xf bank_mask:0xf bound_ctrl:1
	v_pk_fma_f32 v[6:7], v[92:93], v[12:13], v[48:49] op_sel_hi:[1,0,1] neg_lo:[1,0,0] neg_hi:[1,0,0]
	v_pk_fma_f32 v[8:9], v[94:95], v[12:13], v[50:51] op_sel_hi:[1,0,1] neg_lo:[1,0,0] neg_hi:[1,0,0]
	ds_read_b128 v[20:23], v10 offset:33024
	ds_read_b128 v[28:31], v10 offset:33536
	ds_read_b128 v[24:27], v10 offset:33280
	s_waitcnt lgkmcnt(4)
	v_fma_mix_f32 v12, v6, v110, v180 op_sel_hi:[0,1,0]
	v_fma_mix_f32 v12, v7, v110, v12 op_sel:[0,1,0] op_sel_hi:[0,1,0]
	v_fma_mix_f32 v12, v8, v111, v12 op_sel_hi:[0,1,0]
	v_fma_mix_f32 v12, v9, v111, v12 op_sel:[0,1,0] op_sel_hi:[0,1,0]
	v_fma_mix_f32 v136, v6, v90, v180 op_sel_hi:[0,1,0]
	v_fma_mix_f32 v136, v7, v90, v136 op_sel:[0,1,0] op_sel_hi:[0,1,0]
	v_add_f32_dpp v12, v12, v12 row_ror:1 row_mask:0xf bank_mask:0xf bound_ctrl:1
	v_fma_mix_f32 v136, v8, v91, v136 op_sel_hi:[0,1,0]
	v_fma_mix_f32 v136, v9, v91, v136 op_sel:[0,1,0] op_sel_hi:[0,1,0]
	v_add_f32_dpp v12, v12, v12 row_ror:2 row_mask:0xf bank_mask:0xf bound_ctrl:1
	v_pk_fma_f32 v[48:49], v[118:119], v[72:73], v[6:7] op_sel:[0,1,0]
	v_pk_fma_f32 v[50:51], v[120:121], v[72:73], v[8:9] op_sel:[0,1,0]
	v_add_f32_dpp v12, v12, v12 row_ror:4 row_mask:0xf bank_mask:0xf bound_ctrl:1
	global_store_short v[2:3], v62, off
	v_lshl_add_u64 v[2:3], v[2:3], 0, s[84:85]
	v_add_f32_dpp v12, v12, v12 row_ror:8 row_mask:0xf bank_mask:0xf bound_ctrl:1
	v_pk_fma_f32 v[6:7], v[114:115], v[12:13], v[48:49] op_sel_hi:[1,0,1] neg_lo:[1,0,0] neg_hi:[1,0,0]
	v_pk_fma_f32 v[8:9], v[116:117], v[12:13], v[50:51] op_sel_hi:[1,0,1] neg_lo:[1,0,0] neg_hi:[1,0,0]
	v_pk_mul_f32 v[6:7], v[6:7], v[106:107]
	v_pk_mul_f32 v[8:9], v[8:9], v[108:109]
	ds_read_b128 v[36:39], v10 offset:34048
	ds_read_b128 v[44:47], v10 offset:34560
	ds_read_b128 v[40:43], v10 offset:34304
	s_waitcnt lgkmcnt(3)
	v_fma_mix_f32 v12, v6, v20, v180 op_sel_hi:[0,1,0]
	v_fma_mix_f32 v12, v7, v20, v12 op_sel:[0,1,0] op_sel_hi:[0,1,0]
	v_fma_mix_f32 v12, v8, v21, v12 op_sel_hi:[0,1,0]
	v_fma_mix_f32 v12, v9, v21, v12 op_sel:[0,1,0] op_sel_hi:[0,1,0]
	v_fma_mix_f32 v137, v6, v112, v180 op_sel_hi:[0,1,0]
	v_fma_mix_f32 v137, v7, v112, v137 op_sel:[0,1,0] op_sel_hi:[0,1,0]
	v_add_f32_dpp v12, v12, v12 row_ror:1 row_mask:0xf bank_mask:0xf bound_ctrl:1
	v_fma_mix_f32 v137, v8, v113, v137 op_sel_hi:[0,1,0]
	v_fma_mix_f32 v137, v9, v113, v137 op_sel:[0,1,0] op_sel_hi:[0,1,0]
	v_add_f32_dpp v12, v12, v12 row_ror:2 row_mask:0xf bank_mask:0xf bound_ctrl:1
	v_pk_fma_f32 v[48:49], v[28:29], v[66:67], v[6:7] op_sel_hi:[1,0,1]
	v_pk_fma_f32 v[50:51], v[30:31], v[66:67], v[8:9] op_sel_hi:[1,0,1]
	v_add_f32_dpp v12, v12, v12 row_ror:4 row_mask:0xf bank_mask:0xf bound_ctrl:1
	s_nop 1
	v_add_f32_dpp v12, v12, v12 row_ror:8 row_mask:0xf bank_mask:0xf bound_ctrl:1
	v_pk_fma_f32 v[6:7], v[24:25], v[12:13], v[48:49] op_sel_hi:[1,0,1] neg_lo:[1,0,0] neg_hi:[1,0,0]
	v_pk_fma_f32 v[8:9], v[26:27], v[12:13], v[50:51] op_sel_hi:[1,0,1] neg_lo:[1,0,0] neg_hi:[1,0,0]
	ds_read_b128 v[88:91], v10 offset:35072
	ds_read_b128 v[96:99], v10 offset:35584
	ds_read_b128 v[92:95], v10 offset:35328
	s_waitcnt lgkmcnt(3)
	v_fma_mix_f32 v12, v6, v36, v180 op_sel_hi:[0,1,0]
	v_fma_mix_f32 v12, v7, v36, v12 op_sel:[0,1,0] op_sel_hi:[0,1,0]
	v_fma_mix_f32 v12, v8, v37, v12 op_sel_hi:[0,1,0]
	v_fma_mix_f32 v12, v9, v37, v12 op_sel:[0,1,0] op_sel_hi:[0,1,0]
	v_fma_mix_f32 v52, v6, v22, v180 op_sel_hi:[0,1,0]
	v_fma_mix_f32 v52, v7, v22, v52 op_sel:[0,1,0] op_sel_hi:[0,1,0]
	v_add_f32_dpp v12, v12, v12 row_ror:1 row_mask:0xf bank_mask:0xf bound_ctrl:1
	v_fma_mix_f32 v52, v8, v23, v52 op_sel_hi:[0,1,0]
	v_fma_mix_f32 v52, v9, v23, v52 op_sel:[0,1,0] op_sel_hi:[0,1,0]
	v_add_f32_dpp v12, v12, v12 row_ror:2 row_mask:0xf bank_mask:0xf bound_ctrl:1
	v_pk_fma_f32 v[48:49], v[44:45], v[66:67], v[6:7] op_sel:[0,1,0]
	v_pk_fma_f32 v[50:51], v[46:47], v[66:67], v[8:9] op_sel:[0,1,0]
	v_add_f32_dpp v12, v12, v12 row_ror:4 row_mask:0xf bank_mask:0xf bound_ctrl:1
	v_add_f32_dpp v130, v130, v130 row_ror:8 row_mask:0xf bank_mask:0xc
	v_add_f32_dpp v130, v122, v122 row_ror:8 row_mask:0xf bank_mask:0x3
	v_add_f32_dpp v131, v131, v131 row_ror:8 row_mask:0xf bank_mask:0xc
	v_add_f32_dpp v12, v12, v12 row_ror:8 row_mask:0xf bank_mask:0xf bound_ctrl:1
	v_pk_fma_f32 v[6:7], v[40:41], v[12:13], v[48:49] op_sel_hi:[1,0,1] neg_lo:[1,0,0] neg_hi:[1,0,0]
	v_pk_fma_f32 v[8:9], v[42:43], v[12:13], v[50:51] op_sel_hi:[1,0,1] neg_lo:[1,0,0] neg_hi:[1,0,0]
	ds_read_b128 v[110:113], v10 offset:36096
	ds_read_b128 v[106:109], v10 offset:35840
	ds_read_b128 v[118:121], v10 offset:36608
	ds_read_b128 v[114:117], v10 offset:36352
	ds_read_b128 v[70:73], v11 offset:2304
	s_waitcnt lgkmcnt(5)
	v_fma_mix_f32 v12, v6, v88, v180 op_sel_hi:[0,1,0]
	v_fma_mix_f32 v12, v7, v88, v12 op_sel:[0,1,0] op_sel_hi:[0,1,0]
	v_fma_mix_f32 v12, v8, v89, v12 op_sel_hi:[0,1,0]
	v_fma_mix_f32 v12, v9, v89, v12 op_sel:[0,1,0] op_sel_hi:[0,1,0]
	v_fma_mix_f32 v53, v6, v38, v180 op_sel_hi:[0,1,0]
	v_fma_mix_f32 v53, v7, v38, v53 op_sel:[0,1,0] op_sel_hi:[0,1,0]
	v_add_f32_dpp v12, v12, v12 row_ror:1 row_mask:0xf bank_mask:0xf bound_ctrl:1
	v_fma_mix_f32 v53, v8, v39, v53 op_sel_hi:[0,1,0]
	v_fma_mix_f32 v53, v9, v39, v53 op_sel:[0,1,0] op_sel_hi:[0,1,0]
	v_add_f32_dpp v12, v12, v12 row_ror:2 row_mask:0xf bank_mask:0xf bound_ctrl:1
	v_pk_fma_f32 v[48:49], v[96:97], v[68:69], v[6:7] op_sel_hi:[1,0,1]
	v_pk_fma_f32 v[50:51], v[98:99], v[68:69], v[8:9] op_sel_hi:[1,0,1]
	v_add_f32_dpp v12, v12, v12 row_ror:4 row_mask:0xf bank_mask:0xf bound_ctrl:1
	v_add_f32_dpp v131, v123, v123 row_ror:8 row_mask:0xf bank_mask:0x3
	v_add_f32_dpp v132, v132, v132 row_ror:8 row_mask:0xf bank_mask:0xc
	v_add_f32_dpp v132, v124, v124 row_ror:8 row_mask:0xf bank_mask:0x3
	v_add_f32_dpp v12, v12, v12 row_ror:8 row_mask:0xf bank_mask:0xf bound_ctrl:1
	v_pk_fma_f32 v[6:7], v[92:93], v[12:13], v[48:49] op_sel_hi:[1,0,1] neg_lo:[1,0,0] neg_hi:[1,0,0]
	v_pk_fma_f32 v[8:9], v[94:95], v[12:13], v[50:51] op_sel_hi:[1,0,1] neg_lo:[1,0,0] neg_hi:[1,0,0]
	ds_read_b128 v[20:23], v10 offset:37120
	ds_read_b128 v[28:31], v10 offset:37632
	ds_read_b128 v[24:27], v10 offset:37376
	s_waitcnt lgkmcnt(4)
	v_fma_mix_f32 v12, v6, v110, v180 op_sel_hi:[0,1,0]
	v_fma_mix_f32 v12, v7, v110, v12 op_sel:[0,1,0] op_sel_hi:[0,1,0]
	v_fma_mix_f32 v12, v8, v111, v12 op_sel_hi:[0,1,0]
	v_fma_mix_f32 v12, v9, v111, v12 op_sel:[0,1,0] op_sel_hi:[0,1,0]
	v_fma_mix_f32 v54, v6, v90, v180 op_sel_hi:[0,1,0]
	v_fma_mix_f32 v54, v7, v90, v54 op_sel:[0,1,0] op_sel_hi:[0,1,0]
	v_add_f32_dpp v12, v12, v12 row_ror:1 row_mask:0xf bank_mask:0xf bound_ctrl:1
	v_fma_mix_f32 v54, v8, v91, v54 op_sel_hi:[0,1,0]
	v_fma_mix_f32 v54, v9, v91, v54 op_sel:[0,1,0] op_sel_hi:[0,1,0]
	v_add_f32_dpp v12, v12, v12 row_ror:2 row_mask:0xf bank_mask:0xf bound_ctrl:1
	v_pk_fma_f32 v[48:49], v[118:119], v[68:69], v[6:7] op_sel:[0,1,0]
	v_pk_fma_f32 v[50:51], v[120:121], v[68:69], v[8:9] op_sel:[0,1,0]
	v_add_f32_dpp v12, v12, v12 row_ror:4 row_mask:0xf bank_mask:0xf bound_ctrl:1
	v_add_f32_dpp v133, v133, v133 row_ror:8 row_mask:0xf bank_mask:0xc
	v_add_f32_dpp v133, v125, v125 row_ror:8 row_mask:0xf bank_mask:0x3
	v_add_f32_dpp v134, v134, v134 row_ror:8 row_mask:0xf bank_mask:0xc
	v_add_f32_dpp v12, v12, v12 row_ror:8 row_mask:0xf bank_mask:0xf bound_ctrl:1
	v_pk_fma_f32 v[6:7], v[114:115], v[12:13], v[48:49] op_sel_hi:[1,0,1] neg_lo:[1,0,0] neg_hi:[1,0,0]
	v_pk_fma_f32 v[8:9], v[116:117], v[12:13], v[50:51] op_sel_hi:[1,0,1] neg_lo:[1,0,0] neg_hi:[1,0,0]
	v_pk_mul_f32 v[6:7], v[6:7], v[106:107]
	v_pk_mul_f32 v[8:9], v[8:9], v[108:109]
	ds_read_b128 v[36:39], v10 offset:38144
	ds_read_b128 v[44:47], v10 offset:38656
	ds_read_b128 v[40:43], v10 offset:38400
	s_waitcnt lgkmcnt(3)
	v_fma_mix_f32 v12, v6, v20, v180 op_sel_hi:[0,1,0]
	v_fma_mix_f32 v12, v7, v20, v12 op_sel:[0,1,0] op_sel_hi:[0,1,0]
	v_fma_mix_f32 v12, v8, v21, v12 op_sel_hi:[0,1,0]
	v_fma_mix_f32 v12, v9, v21, v12 op_sel:[0,1,0] op_sel_hi:[0,1,0]
	v_fma_mix_f32 v55, v6, v112, v180 op_sel_hi:[0,1,0]
	v_fma_mix_f32 v55, v7, v112, v55 op_sel:[0,1,0] op_sel_hi:[0,1,0]
	v_add_f32_dpp v12, v12, v12 row_ror:1 row_mask:0xf bank_mask:0xf bound_ctrl:1
	v_fma_mix_f32 v55, v8, v113, v55 op_sel_hi:[0,1,0]
	v_fma_mix_f32 v55, v9, v113, v55 op_sel:[0,1,0] op_sel_hi:[0,1,0]
	v_add_f32_dpp v12, v12, v12 row_ror:2 row_mask:0xf bank_mask:0xf bound_ctrl:1
	v_pk_fma_f32 v[48:49], v[28:29], v[70:71], v[6:7] op_sel_hi:[1,0,1]
	v_pk_fma_f32 v[50:51], v[30:31], v[70:71], v[8:9] op_sel_hi:[1,0,1]
	v_add_f32_dpp v12, v12, v12 row_ror:4 row_mask:0xf bank_mask:0xf bound_ctrl:1
	v_add_f32_dpp v134, v126, v126 row_ror:8 row_mask:0xf bank_mask:0x3
	v_add_f32_dpp v135, v135, v135 row_ror:8 row_mask:0xf bank_mask:0xc
	v_add_f32_dpp v135, v127, v127 row_ror:8 row_mask:0xf bank_mask:0x3
	v_add_f32_dpp v12, v12, v12 row_ror:8 row_mask:0xf bank_mask:0xf bound_ctrl:1
	v_pk_fma_f32 v[6:7], v[24:25], v[12:13], v[48:49] op_sel_hi:[1,0,1] neg_lo:[1,0,0] neg_hi:[1,0,0]
	v_pk_fma_f32 v[8:9], v[26:27], v[12:13], v[50:51] op_sel_hi:[1,0,1] neg_lo:[1,0,0] neg_hi:[1,0,0]
	ds_read_b128 v[88:91], v10 offset:39168
	ds_read_b128 v[96:99], v10 offset:39680
	ds_read_b128 v[92:95], v10 offset:39424
	s_waitcnt lgkmcnt(3)
	v_fma_mix_f32 v12, v6, v36, v180 op_sel_hi:[0,1,0]
	v_fma_mix_f32 v12, v7, v36, v12 op_sel:[0,1,0] op_sel_hi:[0,1,0]
	v_fma_mix_f32 v12, v8, v37, v12 op_sel_hi:[0,1,0]
	v_fma_mix_f32 v12, v9, v37, v12 op_sel:[0,1,0] op_sel_hi:[0,1,0]
	v_fma_mix_f32 v56, v6, v22, v180 op_sel_hi:[0,1,0]
	v_fma_mix_f32 v56, v7, v22, v56 op_sel:[0,1,0] op_sel_hi:[0,1,0]
	v_add_f32_dpp v12, v12, v12 row_ror:1 row_mask:0xf bank_mask:0xf bound_ctrl:1
	v_fma_mix_f32 v56, v8, v23, v56 op_sel_hi:[0,1,0]
	v_fma_mix_f32 v56, v9, v23, v56 op_sel:[0,1,0] op_sel_hi:[0,1,0]
	v_add_f32_dpp v12, v12, v12 row_ror:2 row_mask:0xf bank_mask:0xf bound_ctrl:1
	v_pk_fma_f32 v[48:49], v[44:45], v[70:71], v[6:7] op_sel:[0,1,0]
	v_pk_fma_f32 v[50:51], v[46:47], v[70:71], v[8:9] op_sel:[0,1,0]
	v_add_f32_dpp v12, v12, v12 row_ror:4 row_mask:0xf bank_mask:0xf bound_ctrl:1
	v_add_f32_dpp v136, v136, v136 row_ror:8 row_mask:0xf bank_mask:0xc
	v_add_f32_dpp v136, v128, v128 row_ror:8 row_mask:0xf bank_mask:0x3
	v_add_f32_dpp v12, v12, v12 row_ror:8 row_mask:0xf bank_mask:0xf bound_ctrl:1
	v_pk_fma_f32 v[6:7], v[40:41], v[12:13], v[48:49] op_sel_hi:[1,0,1] neg_lo:[1,0,0] neg_hi:[1,0,0]
	v_pk_fma_f32 v[8:9], v[42:43], v[12:13], v[50:51] op_sel_hi:[1,0,1] neg_lo:[1,0,0] neg_hi:[1,0,0]
	ds_read_b128 v[110:113], v10 offset:40192
	ds_read_b128 v[106:109], v10 offset:39936
	ds_read_b128 v[118:121], v10 offset:40704
	ds_read_b128 v[114:117], v10 offset:40448
	ds_read_b128 v[66:69], v11 offset:2560
	s_waitcnt lgkmcnt(5)
	v_fma_mix_f32 v12, v6, v88, v180 op_sel_hi:[0,1,0]
	v_fma_mix_f32 v12, v7, v88, v12 op_sel:[0,1,0] op_sel_hi:[0,1,0]
	v_fma_mix_f32 v12, v8, v89, v12 op_sel_hi:[0,1,0]
	v_fma_mix_f32 v12, v9, v89, v12 op_sel:[0,1,0] op_sel_hi:[0,1,0]
	v_fma_mix_f32 v57, v6, v38, v180 op_sel_hi:[0,1,0]
	v_fma_mix_f32 v57, v7, v38, v57 op_sel:[0,1,0] op_sel_hi:[0,1,0]
	v_add_f32_dpp v12, v12, v12 row_ror:1 row_mask:0xf bank_mask:0xf bound_ctrl:1
	v_fma_mix_f32 v57, v8, v39, v57 op_sel_hi:[0,1,0]
	v_fma_mix_f32 v57, v9, v39, v57 op_sel:[0,1,0] op_sel_hi:[0,1,0]
	v_add_f32_dpp v12, v12, v12 row_ror:2 row_mask:0xf bank_mask:0xf bound_ctrl:1
	v_pk_fma_f32 v[48:49], v[96:97], v[72:73], v[6:7] op_sel_hi:[1,0,1]
	v_pk_fma_f32 v[50:51], v[98:99], v[72:73], v[8:9] op_sel_hi:[1,0,1]
	v_add_f32_dpp v12, v12, v12 row_ror:4 row_mask:0xf bank_mask:0xf bound_ctrl:1
	v_add_f32_dpp v137, v137, v137 row_ror:8 row_mask:0xf bank_mask:0xc
	v_add_f32_dpp v137, v129, v129 row_ror:8 row_mask:0xf bank_mask:0x3
	v_add_f32_dpp v12, v12, v12 row_ror:8 row_mask:0xf bank_mask:0xf bound_ctrl:1
	v_pk_fma_f32 v[6:7], v[92:93], v[12:13], v[48:49] op_sel_hi:[1,0,1] neg_lo:[1,0,0] neg_hi:[1,0,0]
	v_pk_fma_f32 v[8:9], v[94:95], v[12:13], v[50:51] op_sel_hi:[1,0,1] neg_lo:[1,0,0] neg_hi:[1,0,0]
	ds_read_b128 v[20:23], v10 offset:41216
	ds_read_b128 v[28:31], v10 offset:41728
	ds_read_b128 v[24:27], v10 offset:41472
	s_waitcnt lgkmcnt(4)
	v_fma_mix_f32 v12, v6, v110, v180 op_sel_hi:[0,1,0]
	v_fma_mix_f32 v12, v7, v110, v12 op_sel:[0,1,0] op_sel_hi:[0,1,0]
	v_fma_mix_f32 v12, v8, v111, v12 op_sel_hi:[0,1,0]
	v_fma_mix_f32 v12, v9, v111, v12 op_sel:[0,1,0] op_sel_hi:[0,1,0]
	v_fma_mix_f32 v81, v6, v90, v180 op_sel_hi:[0,1,0]
	v_fma_mix_f32 v81, v7, v90, v81 op_sel:[0,1,0] op_sel_hi:[0,1,0]
	v_add_f32_dpp v12, v12, v12 row_ror:1 row_mask:0xf bank_mask:0xf bound_ctrl:1
	v_fma_mix_f32 v81, v8, v91, v81 op_sel_hi:[0,1,0]
	v_fma_mix_f32 v81, v9, v91, v81 op_sel:[0,1,0] op_sel_hi:[0,1,0]
	v_add_f32_dpp v12, v12, v12 row_ror:2 row_mask:0xf bank_mask:0xf bound_ctrl:1
	v_pk_fma_f32 v[48:49], v[118:119], v[72:73], v[6:7] op_sel:[0,1,0]
	v_pk_fma_f32 v[50:51], v[120:121], v[72:73], v[8:9] op_sel:[0,1,0]
	v_add_f32_dpp v12, v12, v12 row_ror:4 row_mask:0xf bank_mask:0xf bound_ctrl:1
	v_add_f32_dpp v134, v134, v134 row_ror:4 row_mask:0xf bank_mask:0xa
	v_add_f32_dpp v134, v130, v130 row_ror:12 row_mask:0xf bank_mask:0x5
	v_add_f32_dpp v135, v135, v135 row_ror:4 row_mask:0xf bank_mask:0xa
	v_add_f32_dpp v12, v12, v12 row_ror:8 row_mask:0xf bank_mask:0xf bound_ctrl:1
	v_pk_fma_f32 v[6:7], v[114:115], v[12:13], v[48:49] op_sel_hi:[1,0,1] neg_lo:[1,0,0] neg_hi:[1,0,0]
	v_pk_fma_f32 v[8:9], v[116:117], v[12:13], v[50:51] op_sel_hi:[1,0,1] neg_lo:[1,0,0] neg_hi:[1,0,0]
	v_pk_mul_f32 v[6:7], v[6:7], v[106:107]
	v_pk_mul_f32 v[8:9], v[8:9], v[108:109]
	ds_read_b128 v[36:39], v10 offset:42240
	ds_read_b128 v[44:47], v10 offset:42752
	ds_read_b128 v[40:43], v10 offset:42496
	s_waitcnt lgkmcnt(3)
	v_fma_mix_f32 v12, v6, v20, v180 op_sel_hi:[0,1,0]
	v_fma_mix_f32 v12, v7, v20, v12 op_sel:[0,1,0] op_sel_hi:[0,1,0]
	v_fma_mix_f32 v12, v8, v21, v12 op_sel_hi:[0,1,0]
	v_fma_mix_f32 v12, v9, v21, v12 op_sel:[0,1,0] op_sel_hi:[0,1,0]
	v_fma_mix_f32 v82, v6, v112, v180 op_sel_hi:[0,1,0]
	v_fma_mix_f32 v82, v7, v112, v82 op_sel:[0,1,0] op_sel_hi:[0,1,0]
	v_add_f32_dpp v12, v12, v12 row_ror:1 row_mask:0xf bank_mask:0xf bound_ctrl:1
	v_fma_mix_f32 v82, v8, v113, v82 op_sel_hi:[0,1,0]
	v_fma_mix_f32 v82, v9, v113, v82 op_sel:[0,1,0] op_sel_hi:[0,1,0]
	v_add_f32_dpp v12, v12, v12 row_ror:2 row_mask:0xf bank_mask:0xf bound_ctrl:1
	v_pk_fma_f32 v[48:49], v[28:29], v[66:67], v[6:7] op_sel_hi:[1,0,1]
	v_pk_fma_f32 v[50:51], v[30:31], v[66:67], v[8:9] op_sel_hi:[1,0,1]
	v_add_f32_dpp v12, v12, v12 row_ror:4 row_mask:0xf bank_mask:0xf bound_ctrl:1
	v_add_f32_dpp v135, v131, v131 row_ror:12 row_mask:0xf bank_mask:0x5
	v_add_f32_dpp v136, v136, v136 row_ror:4 row_mask:0xf bank_mask:0xa
	v_add_f32_dpp v136, v132, v132 row_ror:12 row_mask:0xf bank_mask:0x5
	v_add_f32_dpp v12, v12, v12 row_ror:8 row_mask:0xf bank_mask:0xf bound_ctrl:1
	v_pk_fma_f32 v[6:7], v[24:25], v[12:13], v[48:49] op_sel_hi:[1,0,1] neg_lo:[1,0,0] neg_hi:[1,0,0]
	v_pk_fma_f32 v[8:9], v[26:27], v[12:13], v[50:51] op_sel_hi:[1,0,1] neg_lo:[1,0,0] neg_hi:[1,0,0]
	ds_read_b128 v[88:91], v10 offset:43264
	ds_read_b128 v[96:99], v10 offset:43776
	ds_read_b128 v[92:95], v10 offset:43520
	s_waitcnt lgkmcnt(3)
	v_fma_mix_f32 v12, v6, v36, v180 op_sel_hi:[0,1,0]
	v_fma_mix_f32 v12, v7, v36, v12 op_sel:[0,1,0] op_sel_hi:[0,1,0]
	v_fma_mix_f32 v12, v8, v37, v12 op_sel_hi:[0,1,0]
	v_fma_mix_f32 v12, v9, v37, v12 op_sel:[0,1,0] op_sel_hi:[0,1,0]
	v_fma_mix_f32 v83, v6, v22, v180 op_sel_hi:[0,1,0]
	v_fma_mix_f32 v83, v7, v22, v83 op_sel:[0,1,0] op_sel_hi:[0,1,0]
	v_add_f32_dpp v12, v12, v12 row_ror:1 row_mask:0xf bank_mask:0xf bound_ctrl:1
	v_fma_mix_f32 v83, v8, v23, v83 op_sel_hi:[0,1,0]
	v_fma_mix_f32 v83, v9, v23, v83 op_sel:[0,1,0] op_sel_hi:[0,1,0]
	v_add_f32_dpp v12, v12, v12 row_ror:2 row_mask:0xf bank_mask:0xf bound_ctrl:1
	v_pk_fma_f32 v[48:49], v[44:45], v[66:67], v[6:7] op_sel:[0,1,0]
	v_pk_fma_f32 v[50:51], v[46:47], v[66:67], v[8:9] op_sel:[0,1,0]
	v_add_f32_dpp v12, v12, v12 row_ror:4 row_mask:0xf bank_mask:0xf bound_ctrl:1
	v_add_f32_dpp v137, v137, v137 row_ror:4 row_mask:0xf bank_mask:0xa
	v_add_f32_dpp v137, v133, v133 row_ror:12 row_mask:0xf bank_mask:0x5
	v_add_f32_dpp v12, v12, v12 row_ror:8 row_mask:0xf bank_mask:0xf bound_ctrl:1
	v_pk_fma_f32 v[6:7], v[40:41], v[12:13], v[48:49] op_sel_hi:[1,0,1] neg_lo:[1,0,0] neg_hi:[1,0,0]
	v_pk_fma_f32 v[8:9], v[42:43], v[12:13], v[50:51] op_sel_hi:[1,0,1] neg_lo:[1,0,0] neg_hi:[1,0,0]
	ds_read_b128 v[110:113], v10 offset:44288
	ds_read_b128 v[106:109], v10 offset:44032
	ds_read_b128 v[118:121], v10 offset:44800
	ds_read_b128 v[114:117], v10 offset:44544
	ds_read_b128 v[70:73], v11 offset:2816
	s_waitcnt lgkmcnt(5)
	v_fma_mix_f32 v12, v6, v88, v180 op_sel_hi:[0,1,0]
	v_fma_mix_f32 v12, v7, v88, v12 op_sel:[0,1,0] op_sel_hi:[0,1,0]
	v_fma_mix_f32 v12, v8, v89, v12 op_sel_hi:[0,1,0]
	v_fma_mix_f32 v12, v9, v89, v12 op_sel:[0,1,0] op_sel_hi:[0,1,0]
	v_fma_mix_f32 v100, v6, v38, v180 op_sel_hi:[0,1,0]
	v_fma_mix_f32 v100, v7, v38, v100 op_sel:[0,1,0] op_sel_hi:[0,1,0]
	v_add_f32_dpp v12, v12, v12 row_ror:1 row_mask:0xf bank_mask:0xf bound_ctrl:1
	v_fma_mix_f32 v100, v8, v39, v100 op_sel_hi:[0,1,0]
	v_fma_mix_f32 v100, v9, v39, v100 op_sel:[0,1,0] op_sel_hi:[0,1,0]
	v_add_f32_dpp v12, v12, v12 row_ror:2 row_mask:0xf bank_mask:0xf bound_ctrl:1
	v_pk_fma_f32 v[48:49], v[96:97], v[68:69], v[6:7] op_sel_hi:[1,0,1]
	v_pk_fma_f32 v[50:51], v[98:99], v[68:69], v[8:9] op_sel_hi:[1,0,1]
	v_add_f32_dpp v12, v12, v12 row_ror:4 row_mask:0xf bank_mask:0xf bound_ctrl:1
	v_cndmask_b32_e64 v62, v136, v134, s[38:39]
	v_cndmask_b32_e64 v63, v134, v136, s[38:39]
	v_add_f32_dpp v12, v12, v12 row_ror:8 row_mask:0xf bank_mask:0xf bound_ctrl:1
	v_pk_fma_f32 v[6:7], v[92:93], v[12:13], v[48:49] op_sel_hi:[1,0,1] neg_lo:[1,0,0] neg_hi:[1,0,0]
	v_pk_fma_f32 v[8:9], v[94:95], v[12:13], v[50:51] op_sel_hi:[1,0,1] neg_lo:[1,0,0] neg_hi:[1,0,0]
	ds_read_b128 v[20:23], v10 offset:45312
	ds_read_b128 v[28:31], v10 offset:45824
	ds_read_b128 v[24:27], v10 offset:45568
	s_waitcnt lgkmcnt(4)
	v_fma_mix_f32 v12, v6, v110, v180 op_sel_hi:[0,1,0]
	v_fma_mix_f32 v12, v7, v110, v12 op_sel:[0,1,0] op_sel_hi:[0,1,0]
	v_fma_mix_f32 v12, v8, v111, v12 op_sel_hi:[0,1,0]
	v_fma_mix_f32 v12, v9, v111, v12 op_sel:[0,1,0] op_sel_hi:[0,1,0]
	v_fma_mix_f32 v101, v6, v90, v180 op_sel_hi:[0,1,0]
	v_fma_mix_f32 v101, v7, v90, v101 op_sel:[0,1,0] op_sel_hi:[0,1,0]
	v_add_f32_dpp v12, v12, v12 row_ror:1 row_mask:0xf bank_mask:0xf bound_ctrl:1
	v_fma_mix_f32 v101, v8, v91, v101 op_sel_hi:[0,1,0]
	v_fma_mix_f32 v101, v9, v91, v101 op_sel:[0,1,0] op_sel_hi:[0,1,0]
	v_add_f32_dpp v12, v12, v12 row_ror:2 row_mask:0xf bank_mask:0xf bound_ctrl:1
	v_pk_fma_f32 v[48:49], v[118:119], v[68:69], v[6:7] op_sel:[0,1,0]
	v_pk_fma_f32 v[50:51], v[120:121], v[68:69], v[8:9] op_sel:[0,1,0]
	v_add_f32_dpp v12, v12, v12 row_ror:4 row_mask:0xf bank_mask:0xf bound_ctrl:1
	v_cndmask_b32_e64 v64, v137, v135, s[38:39]
	v_cndmask_b32_e64 v65, v135, v137, s[38:39]
	v_add_f32_dpp v12, v12, v12 row_ror:8 row_mask:0xf bank_mask:0xf bound_ctrl:1
	v_pk_fma_f32 v[6:7], v[114:115], v[12:13], v[48:49] op_sel_hi:[1,0,1] neg_lo:[1,0,0] neg_hi:[1,0,0]
	v_pk_fma_f32 v[8:9], v[116:117], v[12:13], v[50:51] op_sel_hi:[1,0,1] neg_lo:[1,0,0] neg_hi:[1,0,0]
	v_pk_mul_f32 v[6:7], v[6:7], v[106:107]
	v_pk_mul_f32 v[8:9], v[8:9], v[108:109]
	ds_read_b128 v[36:39], v10 offset:46336
	ds_read_b128 v[44:47], v10 offset:46848
	ds_read_b128 v[40:43], v10 offset:46592
	s_waitcnt lgkmcnt(3)
	v_fma_mix_f32 v12, v6, v20, v180 op_sel_hi:[0,1,0]
	v_fma_mix_f32 v12, v7, v20, v12 op_sel:[0,1,0] op_sel_hi:[0,1,0]
	v_fma_mix_f32 v12, v8, v21, v12 op_sel_hi:[0,1,0]
	v_fma_mix_f32 v12, v9, v21, v12 op_sel:[0,1,0] op_sel_hi:[0,1,0]
	v_fma_mix_f32 v102, v6, v112, v180 op_sel_hi:[0,1,0]
	v_fma_mix_f32 v102, v7, v112, v102 op_sel:[0,1,0] op_sel_hi:[0,1,0]
	v_add_f32_dpp v12, v12, v12 row_ror:1 row_mask:0xf bank_mask:0xf bound_ctrl:1
	v_fma_mix_f32 v102, v8, v113, v102 op_sel_hi:[0,1,0]
	v_fma_mix_f32 v102, v9, v113, v102 op_sel:[0,1,0] op_sel_hi:[0,1,0]
	v_add_f32_dpp v12, v12, v12 row_ror:2 row_mask:0xf bank_mask:0xf bound_ctrl:1
	v_pk_fma_f32 v[48:49], v[28:29], v[70:71], v[6:7] op_sel_hi:[1,0,1]
	v_pk_fma_f32 v[50:51], v[30:31], v[70:71], v[8:9] op_sel_hi:[1,0,1]
	v_add_f32_dpp v12, v12, v12 row_ror:4 row_mask:0xf bank_mask:0xf bound_ctrl:1
	v_add_f32_dpp v62, v63, v62 quad_perm:[2,3,0,1] row_mask:0xf bank_mask:0xf bound_ctrl:1
	v_add_f32_dpp v63, v65, v64 quad_perm:[2,3,0,1] row_mask:0xf bank_mask:0xf bound_ctrl:1
	v_add_f32_dpp v12, v12, v12 row_ror:8 row_mask:0xf bank_mask:0xf bound_ctrl:1
	v_pk_fma_f32 v[6:7], v[24:25], v[12:13], v[48:49] op_sel_hi:[1,0,1] neg_lo:[1,0,0] neg_hi:[1,0,0]
	v_pk_fma_f32 v[8:9], v[26:27], v[12:13], v[50:51] op_sel_hi:[1,0,1] neg_lo:[1,0,0] neg_hi:[1,0,0]
	ds_read_b128 v[88:91], v10 offset:47360
	ds_read_b128 v[96:99], v10 offset:47872
	ds_read_b128 v[92:95], v10 offset:47616
	s_waitcnt lgkmcnt(3)
	v_fma_mix_f32 v12, v6, v36, v180 op_sel_hi:[0,1,0]
	v_fma_mix_f32 v12, v7, v36, v12 op_sel:[0,1,0] op_sel_hi:[0,1,0]
	v_fma_mix_f32 v12, v8, v37, v12 op_sel_hi:[0,1,0]
	v_fma_mix_f32 v12, v9, v37, v12 op_sel:[0,1,0] op_sel_hi:[0,1,0]
	v_fma_mix_f32 v103, v6, v22, v180 op_sel_hi:[0,1,0]
	v_fma_mix_f32 v103, v7, v22, v103 op_sel:[0,1,0] op_sel_hi:[0,1,0]
	v_add_f32_dpp v12, v12, v12 row_ror:1 row_mask:0xf bank_mask:0xf bound_ctrl:1
	v_fma_mix_f32 v103, v8, v23, v103 op_sel_hi:[0,1,0]
	v_fma_mix_f32 v103, v9, v23, v103 op_sel:[0,1,0] op_sel_hi:[0,1,0]
	v_add_f32_dpp v12, v12, v12 row_ror:2 row_mask:0xf bank_mask:0xf bound_ctrl:1
	v_pk_fma_f32 v[48:49], v[44:45], v[70:71], v[6:7] op_sel:[0,1,0]
	v_pk_fma_f32 v[50:51], v[46:47], v[70:71], v[8:9] op_sel:[0,1,0]
	v_add_f32_dpp v12, v12, v12 row_ror:4 row_mask:0xf bank_mask:0xf bound_ctrl:1
	v_cndmask_b32_e64 v65, v63, v62, s[40:41]
	v_cndmask_b32_e64 v62, v62, v63, s[40:41]
	v_add_f32_dpp v12, v12, v12 row_ror:8 row_mask:0xf bank_mask:0xf bound_ctrl:1
	v_pk_fma_f32 v[6:7], v[40:41], v[12:13], v[48:49] op_sel_hi:[1,0,1] neg_lo:[1,0,0] neg_hi:[1,0,0]
	v_pk_fma_f32 v[8:9], v[42:43], v[12:13], v[50:51] op_sel_hi:[1,0,1] neg_lo:[1,0,0] neg_hi:[1,0,0]
	ds_read_b128 v[110:113], v10 offset:48384
	ds_read_b128 v[106:109], v10 offset:48128
	ds_read_b128 v[118:121], v10 offset:48896
	ds_read_b128 v[114:117], v10 offset:48640
	ds_read_b128 v[66:69], v11 offset:3072
	s_waitcnt lgkmcnt(5)
	v_fma_mix_f32 v12, v6, v88, v180 op_sel_hi:[0,1,0]
	v_fma_mix_f32 v12, v7, v88, v12 op_sel:[0,1,0] op_sel_hi:[0,1,0]
	v_fma_mix_f32 v12, v8, v89, v12 op_sel_hi:[0,1,0]
	v_fma_mix_f32 v12, v9, v89, v12 op_sel:[0,1,0] op_sel_hi:[0,1,0]
	v_fma_mix_f32 v104, v6, v38, v180 op_sel_hi:[0,1,0]
	v_fma_mix_f32 v104, v7, v38, v104 op_sel:[0,1,0] op_sel_hi:[0,1,0]
	v_add_f32_dpp v12, v12, v12 row_ror:1 row_mask:0xf bank_mask:0xf bound_ctrl:1
	v_fma_mix_f32 v104, v8, v39, v104 op_sel_hi:[0,1,0]
	v_fma_mix_f32 v104, v9, v39, v104 op_sel:[0,1,0] op_sel_hi:[0,1,0]
	v_add_f32_dpp v12, v12, v12 row_ror:2 row_mask:0xf bank_mask:0xf bound_ctrl:1
	v_pk_fma_f32 v[48:49], v[96:97], v[72:73], v[6:7] op_sel_hi:[1,0,1]
	v_pk_fma_f32 v[50:51], v[98:99], v[72:73], v[8:9] op_sel_hi:[1,0,1]
	v_add_f32_dpp v12, v12, v12 row_ror:4 row_mask:0xf bank_mask:0xf bound_ctrl:1
	v_add_f32_dpp v62, v62, v65 quad_perm:[1,0,3,2] row_mask:0xf bank_mask:0xf bound_ctrl:1
	v_cvt_pk_bf16_f32 v62, v62, v62
	v_add_f32_dpp v12, v12, v12 row_ror:8 row_mask:0xf bank_mask:0xf bound_ctrl:1
	v_pk_fma_f32 v[6:7], v[92:93], v[12:13], v[48:49] op_sel_hi:[1,0,1] neg_lo:[1,0,0] neg_hi:[1,0,0]
	v_pk_fma_f32 v[8:9], v[94:95], v[12:13], v[50:51] op_sel_hi:[1,0,1] neg_lo:[1,0,0] neg_hi:[1,0,0]
	ds_read_b128 v[20:23], v10 offset:49408
	ds_read_b128 v[28:31], v10 offset:49920
	ds_read_b128 v[24:27], v10 offset:49664
	s_waitcnt lgkmcnt(4)
	v_fma_mix_f32 v12, v6, v110, v180 op_sel_hi:[0,1,0]
	v_fma_mix_f32 v12, v7, v110, v12 op_sel:[0,1,0] op_sel_hi:[0,1,0]
	v_fma_mix_f32 v12, v8, v111, v12 op_sel_hi:[0,1,0]
	v_fma_mix_f32 v12, v9, v111, v12 op_sel:[0,1,0] op_sel_hi:[0,1,0]
	v_fma_mix_f32 v105, v6, v90, v180 op_sel_hi:[0,1,0]
	v_fma_mix_f32 v105, v7, v90, v105 op_sel:[0,1,0] op_sel_hi:[0,1,0]
	v_add_f32_dpp v12, v12, v12 row_ror:1 row_mask:0xf bank_mask:0xf bound_ctrl:1
	v_fma_mix_f32 v105, v8, v91, v105 op_sel_hi:[0,1,0]
	v_fma_mix_f32 v105, v9, v91, v105 op_sel:[0,1,0] op_sel_hi:[0,1,0]
	v_add_f32_dpp v12, v12, v12 row_ror:2 row_mask:0xf bank_mask:0xf bound_ctrl:1
	v_pk_fma_f32 v[48:49], v[118:119], v[72:73], v[6:7] op_sel:[0,1,0]
	v_pk_fma_f32 v[50:51], v[120:121], v[72:73], v[8:9] op_sel:[0,1,0]
	v_add_f32_dpp v12, v12, v12 row_ror:4 row_mask:0xf bank_mask:0xf bound_ctrl:1
	global_store_short v[2:3], v62, off
	v_lshl_add_u64 v[2:3], v[2:3], 0, s[84:85]
	v_add_f32_dpp v12, v12, v12 row_ror:8 row_mask:0xf bank_mask:0xf bound_ctrl:1
	v_pk_fma_f32 v[6:7], v[114:115], v[12:13], v[48:49] op_sel_hi:[1,0,1] neg_lo:[1,0,0] neg_hi:[1,0,0]
	v_pk_fma_f32 v[8:9], v[116:117], v[12:13], v[50:51] op_sel_hi:[1,0,1] neg_lo:[1,0,0] neg_hi:[1,0,0]
	v_pk_mul_f32 v[6:7], v[6:7], v[106:107]
	v_pk_mul_f32 v[8:9], v[8:9], v[108:109]
	ds_read_b128 v[36:39], v10 offset:50432
	ds_read_b128 v[44:47], v10 offset:50944
	ds_read_b128 v[40:43], v10 offset:50688
	s_waitcnt lgkmcnt(3)
	v_fma_mix_f32 v12, v6, v20, v180 op_sel_hi:[0,1,0]
	v_fma_mix_f32 v12, v7, v20, v12 op_sel:[0,1,0] op_sel_hi:[0,1,0]
	v_fma_mix_f32 v12, v8, v21, v12 op_sel_hi:[0,1,0]
	v_fma_mix_f32 v12, v9, v21, v12 op_sel:[0,1,0] op_sel_hi:[0,1,0]
	v_fma_mix_f32 v61, v6, v112, v180 op_sel_hi:[0,1,0]
	v_fma_mix_f32 v61, v7, v112, v61 op_sel:[0,1,0] op_sel_hi:[0,1,0]
	v_add_f32_dpp v12, v12, v12 row_ror:1 row_mask:0xf bank_mask:0xf bound_ctrl:1
	v_fma_mix_f32 v61, v8, v113, v61 op_sel_hi:[0,1,0]
	v_fma_mix_f32 v61, v9, v113, v61 op_sel:[0,1,0] op_sel_hi:[0,1,0]
	v_add_f32_dpp v12, v12, v12 row_ror:2 row_mask:0xf bank_mask:0xf bound_ctrl:1
	v_pk_fma_f32 v[48:49], v[28:29], v[66:67], v[6:7] op_sel_hi:[1,0,1]
	v_pk_fma_f32 v[50:51], v[30:31], v[66:67], v[8:9] op_sel_hi:[1,0,1]
	v_add_f32_dpp v12, v12, v12 row_ror:4 row_mask:0xf bank_mask:0xf bound_ctrl:1
	s_nop 1
	v_add_f32_dpp v12, v12, v12 row_ror:8 row_mask:0xf bank_mask:0xf bound_ctrl:1
	v_pk_fma_f32 v[6:7], v[24:25], v[12:13], v[48:49] op_sel_hi:[1,0,1] neg_lo:[1,0,0] neg_hi:[1,0,0]
	v_pk_fma_f32 v[8:9], v[26:27], v[12:13], v[50:51] op_sel_hi:[1,0,1] neg_lo:[1,0,0] neg_hi:[1,0,0]
	ds_read_b128 v[88:91], v10 offset:51456
	ds_read_b128 v[96:99], v10 offset:51968
	ds_read_b128 v[92:95], v10 offset:51712
	s_waitcnt lgkmcnt(3)
	v_fma_mix_f32 v12, v6, v36, v180 op_sel_hi:[0,1,0]
	v_fma_mix_f32 v12, v7, v36, v12 op_sel:[0,1,0] op_sel_hi:[0,1,0]
	v_fma_mix_f32 v12, v8, v37, v12 op_sel_hi:[0,1,0]
	v_fma_mix_f32 v12, v9, v37, v12 op_sel:[0,1,0] op_sel_hi:[0,1,0]
	v_fma_mix_f32 v122, v6, v22, v180 op_sel_hi:[0,1,0]
	v_fma_mix_f32 v122, v7, v22, v122 op_sel:[0,1,0] op_sel_hi:[0,1,0]
	v_add_f32_dpp v12, v12, v12 row_ror:1 row_mask:0xf bank_mask:0xf bound_ctrl:1
	v_fma_mix_f32 v122, v8, v23, v122 op_sel_hi:[0,1,0]
	v_fma_mix_f32 v122, v9, v23, v122 op_sel:[0,1,0] op_sel_hi:[0,1,0]
	v_add_f32_dpp v12, v12, v12 row_ror:2 row_mask:0xf bank_mask:0xf bound_ctrl:1
	v_pk_fma_f32 v[48:49], v[44:45], v[66:67], v[6:7] op_sel:[0,1,0]
	v_pk_fma_f32 v[50:51], v[46:47], v[66:67], v[8:9] op_sel:[0,1,0]
	v_add_f32_dpp v12, v12, v12 row_ror:4 row_mask:0xf bank_mask:0xf bound_ctrl:1
	v_add_f32_dpp v83, v83, v83 row_ror:8 row_mask:0xf bank_mask:0xc
	v_add_f32_dpp v83, v52, v52 row_ror:8 row_mask:0xf bank_mask:0x3
	v_add_f32_dpp v100, v100, v100 row_ror:8 row_mask:0xf bank_mask:0xc
	v_add_f32_dpp v12, v12, v12 row_ror:8 row_mask:0xf bank_mask:0xf bound_ctrl:1
	v_pk_fma_f32 v[6:7], v[40:41], v[12:13], v[48:49] op_sel_hi:[1,0,1] neg_lo:[1,0,0] neg_hi:[1,0,0]
	v_pk_fma_f32 v[8:9], v[42:43], v[12:13], v[50:51] op_sel_hi:[1,0,1] neg_lo:[1,0,0] neg_hi:[1,0,0]
	ds_read_b128 v[110:113], v10 offset:52480
	ds_read_b128 v[106:109], v10 offset:52224
	ds_read_b128 v[118:121], v10 offset:52992
	ds_read_b128 v[114:117], v10 offset:52736
	ds_read_b128 v[70:73], v11 offset:3328
	s_waitcnt lgkmcnt(5)
	v_fma_mix_f32 v12, v6, v88, v180 op_sel_hi:[0,1,0]
	v_fma_mix_f32 v12, v7, v88, v12 op_sel:[0,1,0] op_sel_hi:[0,1,0]
	v_fma_mix_f32 v12, v8, v89, v12 op_sel_hi:[0,1,0]
	v_fma_mix_f32 v12, v9, v89, v12 op_sel:[0,1,0] op_sel_hi:[0,1,0]
	v_fma_mix_f32 v123, v6, v38, v180 op_sel_hi:[0,1,0]
	v_fma_mix_f32 v123, v7, v38, v123 op_sel:[0,1,0] op_sel_hi:[0,1,0]
	v_add_f32_dpp v12, v12, v12 row_ror:1 row_mask:0xf bank_mask:0xf bound_ctrl:1
	v_fma_mix_f32 v123, v8, v39, v123 op_sel_hi:[0,1,0]
	v_fma_mix_f32 v123, v9, v39, v123 op_sel:[0,1,0] op_sel_hi:[0,1,0]
	v_add_f32_dpp v12, v12, v12 row_ror:2 row_mask:0xf bank_mask:0xf bound_ctrl:1
	v_pk_fma_f32 v[48:49], v[96:97], v[68:69], v[6:7] op_sel_hi:[1,0,1]
	v_pk_fma_f32 v[50:51], v[98:99], v[68:69], v[8:9] op_sel_hi:[1,0,1]
	v_add_f32_dpp v12, v12, v12 row_ror:4 row_mask:0xf bank_mask:0xf bound_ctrl:1
	v_add_f32_dpp v100, v53, v53 row_ror:8 row_mask:0xf bank_mask:0x3
	v_add_f32_dpp v101, v101, v101 row_ror:8 row_mask:0xf bank_mask:0xc
	v_add_f32_dpp v101, v54, v54 row_ror:8 row_mask:0xf bank_mask:0x3
	v_add_f32_dpp v12, v12, v12 row_ror:8 row_mask:0xf bank_mask:0xf bound_ctrl:1
	v_pk_fma_f32 v[6:7], v[92:93], v[12:13], v[48:49] op_sel_hi:[1,0,1] neg_lo:[1,0,0] neg_hi:[1,0,0]
	v_pk_fma_f32 v[8:9], v[94:95], v[12:13], v[50:51] op_sel_hi:[1,0,1] neg_lo:[1,0,0] neg_hi:[1,0,0]
	ds_read_b128 v[20:23], v10 offset:53504
	ds_read_b128 v[28:31], v10 offset:54016
	ds_read_b128 v[24:27], v10 offset:53760
	s_waitcnt lgkmcnt(4)
	v_fma_mix_f32 v12, v6, v110, v180 op_sel_hi:[0,1,0]
	v_fma_mix_f32 v12, v7, v110, v12 op_sel:[0,1,0] op_sel_hi:[0,1,0]
	v_fma_mix_f32 v12, v8, v111, v12 op_sel_hi:[0,1,0]
	v_fma_mix_f32 v12, v9, v111, v12 op_sel:[0,1,0] op_sel_hi:[0,1,0]
	v_fma_mix_f32 v124, v6, v90, v180 op_sel_hi:[0,1,0]
	v_fma_mix_f32 v124, v7, v90, v124 op_sel:[0,1,0] op_sel_hi:[0,1,0]
	v_add_f32_dpp v12, v12, v12 row_ror:1 row_mask:0xf bank_mask:0xf bound_ctrl:1
	v_fma_mix_f32 v124, v8, v91, v124 op_sel_hi:[0,1,0]
	v_fma_mix_f32 v124, v9, v91, v124 op_sel:[0,1,0] op_sel_hi:[0,1,0]
	v_add_f32_dpp v12, v12, v12 row_ror:2 row_mask:0xf bank_mask:0xf bound_ctrl:1
	v_pk_fma_f32 v[48:49], v[118:119], v[68:69], v[6:7] op_sel:[0,1,0]
	v_pk_fma_f32 v[50:51], v[120:121], v[68:69], v[8:9] op_sel:[0,1,0]
	v_add_f32_dpp v12, v12, v12 row_ror:4 row_mask:0xf bank_mask:0xf bound_ctrl:1
	v_add_f32_dpp v102, v102, v102 row_ror:8 row_mask:0xf bank_mask:0xc
	v_add_f32_dpp v102, v55, v55 row_ror:8 row_mask:0xf bank_mask:0x3
	v_add_f32_dpp v103, v103, v103 row_ror:8 row_mask:0xf bank_mask:0xc
	v_add_f32_dpp v12, v12, v12 row_ror:8 row_mask:0xf bank_mask:0xf bound_ctrl:1
	v_pk_fma_f32 v[6:7], v[114:115], v[12:13], v[48:49] op_sel_hi:[1,0,1] neg_lo:[1,0,0] neg_hi:[1,0,0]
	v_pk_fma_f32 v[8:9], v[116:117], v[12:13], v[50:51] op_sel_hi:[1,0,1] neg_lo:[1,0,0] neg_hi:[1,0,0]
	v_pk_mul_f32 v[6:7], v[6:7], v[106:107]
	v_pk_mul_f32 v[8:9], v[8:9], v[108:109]
	ds_read_b128 v[36:39], v10 offset:54528
	ds_read_b128 v[44:47], v10 offset:55040
	ds_read_b128 v[40:43], v10 offset:54784
	s_waitcnt lgkmcnt(3)
	v_fma_mix_f32 v12, v6, v20, v180 op_sel_hi:[0,1,0]
	v_fma_mix_f32 v12, v7, v20, v12 op_sel:[0,1,0] op_sel_hi:[0,1,0]
	v_fma_mix_f32 v12, v8, v21, v12 op_sel_hi:[0,1,0]
	v_fma_mix_f32 v12, v9, v21, v12 op_sel:[0,1,0] op_sel_hi:[0,1,0]
	v_fma_mix_f32 v125, v6, v112, v180 op_sel_hi:[0,1,0]
	v_fma_mix_f32 v125, v7, v112, v125 op_sel:[0,1,0] op_sel_hi:[0,1,0]
	v_add_f32_dpp v12, v12, v12 row_ror:1 row_mask:0xf bank_mask:0xf bound_ctrl:1
	v_fma_mix_f32 v125, v8, v113, v125 op_sel_hi:[0,1,0]
	v_fma_mix_f32 v125, v9, v113, v125 op_sel:[0,1,0] op_sel_hi:[0,1,0]
	v_add_f32_dpp v12, v12, v12 row_ror:2 row_mask:0xf bank_mask:0xf bound_ctrl:1
	v_pk_fma_f32 v[48:49], v[28:29], v[70:71], v[6:7] op_sel_hi:[1,0,1]
	v_pk_fma_f32 v[50:51], v[30:31], v[70:71], v[8:9] op_sel_hi:[1,0,1]
	v_add_f32_dpp v12, v12, v12 row_ror:4 row_mask:0xf bank_mask:0xf bound_ctrl:1
	v_add_f32_dpp v103, v56, v56 row_ror:8 row_mask:0xf bank_mask:0x3
	v_add_f32_dpp v104, v104, v104 row_ror:8 row_mask:0xf bank_mask:0xc
	v_add_f32_dpp v104, v57, v57 row_ror:8 row_mask:0xf bank_mask:0x3
	v_add_f32_dpp v12, v12, v12 row_ror:8 row_mask:0xf bank_mask:0xf bound_ctrl:1
	v_pk_fma_f32 v[6:7], v[24:25], v[12:13], v[48:49] op_sel_hi:[1,0,1] neg_lo:[1,0,0] neg_hi:[1,0,0]
	v_pk_fma_f32 v[8:9], v[26:27], v[12:13], v[50:51] op_sel_hi:[1,0,1] neg_lo:[1,0,0] neg_hi:[1,0,0]
	ds_read_b128 v[88:91], v10 offset:55552
	ds_read_b128 v[96:99], v10 offset:56064
	ds_read_b128 v[92:95], v10 offset:55808
	s_waitcnt lgkmcnt(3)
	v_fma_mix_f32 v12, v6, v36, v180 op_sel_hi:[0,1,0]
	v_fma_mix_f32 v12, v7, v36, v12 op_sel:[0,1,0] op_sel_hi:[0,1,0]
	v_fma_mix_f32 v12, v8, v37, v12 op_sel_hi:[0,1,0]
	v_fma_mix_f32 v12, v9, v37, v12 op_sel:[0,1,0] op_sel_hi:[0,1,0]
	v_fma_mix_f32 v126, v6, v22, v180 op_sel_hi:[0,1,0]
	v_fma_mix_f32 v126, v7, v22, v126 op_sel:[0,1,0] op_sel_hi:[0,1,0]
	v_add_f32_dpp v12, v12, v12 row_ror:1 row_mask:0xf bank_mask:0xf bound_ctrl:1
	v_fma_mix_f32 v126, v8, v23, v126 op_sel_hi:[0,1,0]
	v_fma_mix_f32 v126, v9, v23, v126 op_sel:[0,1,0] op_sel_hi:[0,1,0]
	v_add_f32_dpp v12, v12, v12 row_ror:2 row_mask:0xf bank_mask:0xf bound_ctrl:1
	v_pk_fma_f32 v[48:49], v[44:45], v[70:71], v[6:7] op_sel:[0,1,0]
	v_pk_fma_f32 v[50:51], v[46:47], v[70:71], v[8:9] op_sel:[0,1,0]
	v_add_f32_dpp v12, v12, v12 row_ror:4 row_mask:0xf bank_mask:0xf bound_ctrl:1
	v_add_f32_dpp v105, v105, v105 row_ror:8 row_mask:0xf bank_mask:0xc
	v_add_f32_dpp v105, v81, v81 row_ror:8 row_mask:0xf bank_mask:0x3
	v_add_f32_dpp v12, v12, v12 row_ror:8 row_mask:0xf bank_mask:0xf bound_ctrl:1
	v_pk_fma_f32 v[6:7], v[40:41], v[12:13], v[48:49] op_sel_hi:[1,0,1] neg_lo:[1,0,0] neg_hi:[1,0,0]
	v_pk_fma_f32 v[8:9], v[42:43], v[12:13], v[50:51] op_sel_hi:[1,0,1] neg_lo:[1,0,0] neg_hi:[1,0,0]
	ds_read_b128 v[110:113], v10 offset:56576
	ds_read_b128 v[106:109], v10 offset:56320
	ds_read_b128 v[118:121], v10 offset:57088
	ds_read_b128 v[114:117], v10 offset:56832
	ds_read_b128 v[66:69], v11 offset:3584
	s_waitcnt lgkmcnt(5)
	v_fma_mix_f32 v12, v6, v88, v180 op_sel_hi:[0,1,0]
	v_fma_mix_f32 v12, v7, v88, v12 op_sel:[0,1,0] op_sel_hi:[0,1,0]
	v_fma_mix_f32 v12, v8, v89, v12 op_sel_hi:[0,1,0]
	v_fma_mix_f32 v12, v9, v89, v12 op_sel:[0,1,0] op_sel_hi:[0,1,0]
	v_fma_mix_f32 v127, v6, v38, v180 op_sel_hi:[0,1,0]
	v_fma_mix_f32 v127, v7, v38, v127 op_sel:[0,1,0] op_sel_hi:[0,1,0]
	v_add_f32_dpp v12, v12, v12 row_ror:1 row_mask:0xf bank_mask:0xf bound_ctrl:1
	v_fma_mix_f32 v127, v8, v39, v127 op_sel_hi:[0,1,0]
	v_fma_mix_f32 v127, v9, v39, v127 op_sel:[0,1,0] op_sel_hi:[0,1,0]
	v_add_f32_dpp v12, v12, v12 row_ror:2 row_mask:0xf bank_mask:0xf bound_ctrl:1
	v_pk_fma_f32 v[48:49], v[96:97], v[72:73], v[6:7] op_sel_hi:[1,0,1]
	v_pk_fma_f32 v[50:51], v[98:99], v[72:73], v[8:9] op_sel_hi:[1,0,1]
	v_add_f32_dpp v12, v12, v12 row_ror:4 row_mask:0xf bank_mask:0xf bound_ctrl:1
	v_add_f32_dpp v61, v61, v61 row_ror:8 row_mask:0xf bank_mask:0xc
	v_add_f32_dpp v61, v82, v82 row_ror:8 row_mask:0xf bank_mask:0x3
	v_add_f32_dpp v12, v12, v12 row_ror:8 row_mask:0xf bank_mask:0xf bound_ctrl:1
	v_pk_fma_f32 v[6:7], v[92:93], v[12:13], v[48:49] op_sel_hi:[1,0,1] neg_lo:[1,0,0] neg_hi:[1,0,0]
	v_pk_fma_f32 v[8:9], v[94:95], v[12:13], v[50:51] op_sel_hi:[1,0,1] neg_lo:[1,0,0] neg_hi:[1,0,0]
	ds_read_b128 v[20:23], v10 offset:57600
	ds_read_b128 v[28:31], v10 offset:58112
	ds_read_b128 v[24:27], v10 offset:57856
	s_waitcnt lgkmcnt(4)
	v_fma_mix_f32 v12, v6, v110, v180 op_sel_hi:[0,1,0]
	v_fma_mix_f32 v12, v7, v110, v12 op_sel:[0,1,0] op_sel_hi:[0,1,0]
	v_fma_mix_f32 v12, v8, v111, v12 op_sel_hi:[0,1,0]
	v_fma_mix_f32 v12, v9, v111, v12 op_sel:[0,1,0] op_sel_hi:[0,1,0]
	v_fma_mix_f32 v128, v6, v90, v180 op_sel_hi:[0,1,0]
	v_fma_mix_f32 v128, v7, v90, v128 op_sel:[0,1,0] op_sel_hi:[0,1,0]
	v_add_f32_dpp v12, v12, v12 row_ror:1 row_mask:0xf bank_mask:0xf bound_ctrl:1
	v_fma_mix_f32 v128, v8, v91, v128 op_sel_hi:[0,1,0]
	v_fma_mix_f32 v128, v9, v91, v128 op_sel:[0,1,0] op_sel_hi:[0,1,0]
	v_add_f32_dpp v12, v12, v12 row_ror:2 row_mask:0xf bank_mask:0xf bound_ctrl:1
	v_pk_fma_f32 v[48:49], v[118:119], v[72:73], v[6:7] op_sel:[0,1,0]
	v_pk_fma_f32 v[50:51], v[120:121], v[72:73], v[8:9] op_sel:[0,1,0]
	v_add_f32_dpp v12, v12, v12 row_ror:4 row_mask:0xf bank_mask:0xf bound_ctrl:1
	v_add_f32_dpp v103, v103, v103 row_ror:4 row_mask:0xf bank_mask:0xa
	v_add_f32_dpp v103, v83, v83 row_ror:12 row_mask:0xf bank_mask:0x5
	v_add_f32_dpp v104, v104, v104 row_ror:4 row_mask:0xf bank_mask:0xa
	v_add_f32_dpp v12, v12, v12 row_ror:8 row_mask:0xf bank_mask:0xf bound_ctrl:1
	v_pk_fma_f32 v[6:7], v[114:115], v[12:13], v[48:49] op_sel_hi:[1,0,1] neg_lo:[1,0,0] neg_hi:[1,0,0]
	v_pk_fma_f32 v[8:9], v[116:117], v[12:13], v[50:51] op_sel_hi:[1,0,1] neg_lo:[1,0,0] neg_hi:[1,0,0]
	v_pk_mul_f32 v[6:7], v[6:7], v[106:107]
	v_pk_mul_f32 v[8:9], v[8:9], v[108:109]
	ds_read_b128 v[36:39], v10 offset:58624
	ds_read_b128 v[44:47], v10 offset:59136
	ds_read_b128 v[40:43], v10 offset:58880
	s_waitcnt lgkmcnt(3)
	v_fma_mix_f32 v12, v6, v20, v180 op_sel_hi:[0,1,0]
	v_fma_mix_f32 v12, v7, v20, v12 op_sel:[0,1,0] op_sel_hi:[0,1,0]
	v_fma_mix_f32 v12, v8, v21, v12 op_sel_hi:[0,1,0]
	v_fma_mix_f32 v12, v9, v21, v12 op_sel:[0,1,0] op_sel_hi:[0,1,0]
	v_fma_mix_f32 v129, v6, v112, v180 op_sel_hi:[0,1,0]
	v_fma_mix_f32 v129, v7, v112, v129 op_sel:[0,1,0] op_sel_hi:[0,1,0]
	v_add_f32_dpp v12, v12, v12 row_ror:1 row_mask:0xf bank_mask:0xf bound_ctrl:1
	v_fma_mix_f32 v129, v8, v113, v129 op_sel_hi:[0,1,0]
	v_fma_mix_f32 v129, v9, v113, v129 op_sel:[0,1,0] op_sel_hi:[0,1,0]
	v_add_f32_dpp v12, v12, v12 row_ror:2 row_mask:0xf bank_mask:0xf bound_ctrl:1
	v_pk_fma_f32 v[48:49], v[28:29], v[66:67], v[6:7] op_sel_hi:[1,0,1]
	v_pk_fma_f32 v[50:51], v[30:31], v[66:67], v[8:9] op_sel_hi:[1,0,1]
	v_add_f32_dpp v12, v12, v12 row_ror:4 row_mask:0xf bank_mask:0xf bound_ctrl:1
	v_add_f32_dpp v104, v100, v100 row_ror:12 row_mask:0xf bank_mask:0x5
	v_add_f32_dpp v105, v105, v105 row_ror:4 row_mask:0xf bank_mask:0xa
	v_add_f32_dpp v105, v101, v101 row_ror:12 row_mask:0xf bank_mask:0x5
	v_add_f32_dpp v12, v12, v12 row_ror:8 row_mask:0xf bank_mask:0xf bound_ctrl:1
	v_pk_fma_f32 v[6:7], v[24:25], v[12:13], v[48:49] op_sel_hi:[1,0,1] neg_lo:[1,0,0] neg_hi:[1,0,0]
	v_pk_fma_f32 v[8:9], v[26:27], v[12:13], v[50:51] op_sel_hi:[1,0,1] neg_lo:[1,0,0] neg_hi:[1,0,0]
	ds_read_b128 v[88:91], v10 offset:59648
	ds_read_b128 v[96:99], v10 offset:60160
	ds_read_b128 v[92:95], v10 offset:59904
	s_waitcnt lgkmcnt(3)
	v_fma_mix_f32 v12, v6, v36, v180 op_sel_hi:[0,1,0]
	v_fma_mix_f32 v12, v7, v36, v12 op_sel:[0,1,0] op_sel_hi:[0,1,0]
	v_fma_mix_f32 v12, v8, v37, v12 op_sel_hi:[0,1,0]
	v_fma_mix_f32 v12, v9, v37, v12 op_sel:[0,1,0] op_sel_hi:[0,1,0]
	v_fma_mix_f32 v130, v6, v22, v180 op_sel_hi:[0,1,0]
	v_fma_mix_f32 v130, v7, v22, v130 op_sel:[0,1,0] op_sel_hi:[0,1,0]
	v_add_f32_dpp v12, v12, v12 row_ror:1 row_mask:0xf bank_mask:0xf bound_ctrl:1
	v_fma_mix_f32 v130, v8, v23, v130 op_sel_hi:[0,1,0]
	v_fma_mix_f32 v130, v9, v23, v130 op_sel:[0,1,0] op_sel_hi:[0,1,0]
	v_add_f32_dpp v12, v12, v12 row_ror:2 row_mask:0xf bank_mask:0xf bound_ctrl:1
	v_pk_fma_f32 v[48:49], v[44:45], v[66:67], v[6:7] op_sel:[0,1,0]
	v_pk_fma_f32 v[50:51], v[46:47], v[66:67], v[8:9] op_sel:[0,1,0]
	v_add_f32_dpp v12, v12, v12 row_ror:4 row_mask:0xf bank_mask:0xf bound_ctrl:1
	v_add_f32_dpp v61, v61, v61 row_ror:4 row_mask:0xf bank_mask:0xa
	v_add_f32_dpp v61, v102, v102 row_ror:12 row_mask:0xf bank_mask:0x5
	v_add_f32_dpp v12, v12, v12 row_ror:8 row_mask:0xf bank_mask:0xf bound_ctrl:1
	v_pk_fma_f32 v[6:7], v[40:41], v[12:13], v[48:49] op_sel_hi:[1,0,1] neg_lo:[1,0,0] neg_hi:[1,0,0]
	v_pk_fma_f32 v[8:9], v[42:43], v[12:13], v[50:51] op_sel_hi:[1,0,1] neg_lo:[1,0,0] neg_hi:[1,0,0]
	ds_read_b128 v[110:113], v10 offset:60672
	ds_read_b128 v[106:109], v10 offset:60416
	ds_read_b128 v[118:121], v10 offset:61184
	ds_read_b128 v[114:117], v10 offset:60928
	ds_read_b128 v[70:73], v11 offset:3840
	s_waitcnt lgkmcnt(5)
	v_fma_mix_f32 v12, v6, v88, v180 op_sel_hi:[0,1,0]
	v_fma_mix_f32 v12, v7, v88, v12 op_sel:[0,1,0] op_sel_hi:[0,1,0]
	v_fma_mix_f32 v12, v8, v89, v12 op_sel_hi:[0,1,0]
	v_fma_mix_f32 v12, v9, v89, v12 op_sel:[0,1,0] op_sel_hi:[0,1,0]
	v_fma_mix_f32 v131, v6, v38, v180 op_sel_hi:[0,1,0]
	v_fma_mix_f32 v131, v7, v38, v131 op_sel:[0,1,0] op_sel_hi:[0,1,0]
	v_add_f32_dpp v12, v12, v12 row_ror:1 row_mask:0xf bank_mask:0xf bound_ctrl:1
	v_fma_mix_f32 v131, v8, v39, v131 op_sel_hi:[0,1,0]
	v_fma_mix_f32 v131, v9, v39, v131 op_sel:[0,1,0] op_sel_hi:[0,1,0]
	v_add_f32_dpp v12, v12, v12 row_ror:2 row_mask:0xf bank_mask:0xf bound_ctrl:1
	v_pk_fma_f32 v[48:49], v[96:97], v[68:69], v[6:7] op_sel_hi:[1,0,1]
	v_pk_fma_f32 v[50:51], v[98:99], v[68:69], v[8:9] op_sel_hi:[1,0,1]
	v_add_f32_dpp v12, v12, v12 row_ror:4 row_mask:0xf bank_mask:0xf bound_ctrl:1
	v_cndmask_b32_e64 v62, v105, v103, s[38:39]
	v_cndmask_b32_e64 v63, v103, v105, s[38:39]
	v_add_f32_dpp v12, v12, v12 row_ror:8 row_mask:0xf bank_mask:0xf bound_ctrl:1
	v_pk_fma_f32 v[6:7], v[92:93], v[12:13], v[48:49] op_sel_hi:[1,0,1] neg_lo:[1,0,0] neg_hi:[1,0,0]
	v_pk_fma_f32 v[8:9], v[94:95], v[12:13], v[50:51] op_sel_hi:[1,0,1] neg_lo:[1,0,0] neg_hi:[1,0,0]
	ds_read_b128 v[20:23], v10 offset:61696
	ds_read_b128 v[28:31], v10 offset:62208
	ds_read_b128 v[24:27], v10 offset:61952
	s_waitcnt lgkmcnt(4)
	v_fma_mix_f32 v12, v6, v110, v180 op_sel_hi:[0,1,0]
	v_fma_mix_f32 v12, v7, v110, v12 op_sel:[0,1,0] op_sel_hi:[0,1,0]
	v_fma_mix_f32 v12, v8, v111, v12 op_sel_hi:[0,1,0]
	v_fma_mix_f32 v12, v9, v111, v12 op_sel:[0,1,0] op_sel_hi:[0,1,0]
	v_fma_mix_f32 v132, v6, v90, v180 op_sel_hi:[0,1,0]
	v_fma_mix_f32 v132, v7, v90, v132 op_sel:[0,1,0] op_sel_hi:[0,1,0]
	v_add_f32_dpp v12, v12, v12 row_ror:1 row_mask:0xf bank_mask:0xf bound_ctrl:1
	v_fma_mix_f32 v132, v8, v91, v132 op_sel_hi:[0,1,0]
	v_fma_mix_f32 v132, v9, v91, v132 op_sel:[0,1,0] op_sel_hi:[0,1,0]
	v_add_f32_dpp v12, v12, v12 row_ror:2 row_mask:0xf bank_mask:0xf bound_ctrl:1
	v_pk_fma_f32 v[48:49], v[118:119], v[68:69], v[6:7] op_sel:[0,1,0]
	v_pk_fma_f32 v[50:51], v[120:121], v[68:69], v[8:9] op_sel:[0,1,0]
	v_add_f32_dpp v12, v12, v12 row_ror:4 row_mask:0xf bank_mask:0xf bound_ctrl:1
	v_cndmask_b32_e64 v64, v61, v104, s[38:39]
	v_cndmask_b32_e64 v65, v104, v61, s[38:39]
	v_add_f32_dpp v12, v12, v12 row_ror:8 row_mask:0xf bank_mask:0xf bound_ctrl:1
	v_pk_fma_f32 v[6:7], v[114:115], v[12:13], v[48:49] op_sel_hi:[1,0,1] neg_lo:[1,0,0] neg_hi:[1,0,0]
	v_pk_fma_f32 v[8:9], v[116:117], v[12:13], v[50:51] op_sel_hi:[1,0,1] neg_lo:[1,0,0] neg_hi:[1,0,0]
	v_pk_mul_f32 v[6:7], v[6:7], v[106:107]
	v_pk_mul_f32 v[8:9], v[8:9], v[108:109]
	ds_read_b128 v[36:39], v10 offset:62720
	ds_read_b128 v[44:47], v10 offset:63232
	ds_read_b128 v[40:43], v10 offset:62976
	s_waitcnt lgkmcnt(3)
	v_fma_mix_f32 v12, v6, v20, v180 op_sel_hi:[0,1,0]
	v_fma_mix_f32 v12, v7, v20, v12 op_sel:[0,1,0] op_sel_hi:[0,1,0]
	v_fma_mix_f32 v12, v8, v21, v12 op_sel_hi:[0,1,0]
	v_fma_mix_f32 v12, v9, v21, v12 op_sel:[0,1,0] op_sel_hi:[0,1,0]
	v_fma_mix_f32 v133, v6, v112, v180 op_sel_hi:[0,1,0]
	v_fma_mix_f32 v133, v7, v112, v133 op_sel:[0,1,0] op_sel_hi:[0,1,0]
	v_add_f32_dpp v12, v12, v12 row_ror:1 row_mask:0xf bank_mask:0xf bound_ctrl:1
	v_fma_mix_f32 v133, v8, v113, v133 op_sel_hi:[0,1,0]
	v_fma_mix_f32 v133, v9, v113, v133 op_sel:[0,1,0] op_sel_hi:[0,1,0]
	v_add_f32_dpp v12, v12, v12 row_ror:2 row_mask:0xf bank_mask:0xf bound_ctrl:1
	v_pk_fma_f32 v[48:49], v[28:29], v[70:71], v[6:7] op_sel_hi:[1,0,1]
	v_pk_fma_f32 v[50:51], v[30:31], v[70:71], v[8:9] op_sel_hi:[1,0,1]
	v_add_f32_dpp v12, v12, v12 row_ror:4 row_mask:0xf bank_mask:0xf bound_ctrl:1
	v_add_f32_dpp v62, v63, v62 quad_perm:[2,3,0,1] row_mask:0xf bank_mask:0xf bound_ctrl:1
	v_add_f32_dpp v63, v65, v64 quad_perm:[2,3,0,1] row_mask:0xf bank_mask:0xf bound_ctrl:1
	v_add_f32_dpp v12, v12, v12 row_ror:8 row_mask:0xf bank_mask:0xf bound_ctrl:1
	v_pk_fma_f32 v[6:7], v[24:25], v[12:13], v[48:49] op_sel_hi:[1,0,1] neg_lo:[1,0,0] neg_hi:[1,0,0]
	v_pk_fma_f32 v[8:9], v[26:27], v[12:13], v[50:51] op_sel_hi:[1,0,1] neg_lo:[1,0,0] neg_hi:[1,0,0]
	ds_read_b128 v[88:91], v10 offset:63744
	ds_read_b128 v[96:99], v10 offset:64256
	ds_read_b128 v[92:95], v10 offset:64000
	s_waitcnt lgkmcnt(3)
	v_fma_mix_f32 v12, v6, v36, v180 op_sel_hi:[0,1,0]
	v_fma_mix_f32 v12, v7, v36, v12 op_sel:[0,1,0] op_sel_hi:[0,1,0]
	v_fma_mix_f32 v12, v8, v37, v12 op_sel_hi:[0,1,0]
	v_fma_mix_f32 v12, v9, v37, v12 op_sel:[0,1,0] op_sel_hi:[0,1,0]
	v_fma_mix_f32 v134, v6, v22, v180 op_sel_hi:[0,1,0]
	v_fma_mix_f32 v134, v7, v22, v134 op_sel:[0,1,0] op_sel_hi:[0,1,0]
	v_add_f32_dpp v12, v12, v12 row_ror:1 row_mask:0xf bank_mask:0xf bound_ctrl:1
	v_fma_mix_f32 v134, v8, v23, v134 op_sel_hi:[0,1,0]
	v_fma_mix_f32 v134, v9, v23, v134 op_sel:[0,1,0] op_sel_hi:[0,1,0]
	v_add_f32_dpp v12, v12, v12 row_ror:2 row_mask:0xf bank_mask:0xf bound_ctrl:1
	v_pk_fma_f32 v[48:49], v[44:45], v[70:71], v[6:7] op_sel:[0,1,0]
	v_pk_fma_f32 v[50:51], v[46:47], v[70:71], v[8:9] op_sel:[0,1,0]
	v_add_f32_dpp v12, v12, v12 row_ror:4 row_mask:0xf bank_mask:0xf bound_ctrl:1
	v_cndmask_b32_e64 v65, v63, v62, s[40:41]
	v_cndmask_b32_e64 v62, v62, v63, s[40:41]
	v_add_f32_dpp v12, v12, v12 row_ror:8 row_mask:0xf bank_mask:0xf bound_ctrl:1
	v_pk_fma_f32 v[6:7], v[40:41], v[12:13], v[48:49] op_sel_hi:[1,0,1] neg_lo:[1,0,0] neg_hi:[1,0,0]
	v_pk_fma_f32 v[8:9], v[42:43], v[12:13], v[50:51] op_sel_hi:[1,0,1] neg_lo:[1,0,0] neg_hi:[1,0,0]
	ds_read_b128 v[110:113], v10 offset:64768
	ds_read_b128 v[106:109], v10 offset:64512
	ds_read_b128 v[118:121], v10 offset:65280
	ds_read_b128 v[114:117], v10 offset:65024
	s_waitcnt lgkmcnt(4)
	v_fma_mix_f32 v12, v6, v88, v180 op_sel_hi:[0,1,0]
	v_fma_mix_f32 v12, v7, v88, v12 op_sel:[0,1,0] op_sel_hi:[0,1,0]
	v_fma_mix_f32 v12, v8, v89, v12 op_sel_hi:[0,1,0]
	v_fma_mix_f32 v12, v9, v89, v12 op_sel:[0,1,0] op_sel_hi:[0,1,0]
	v_fma_mix_f32 v135, v6, v38, v180 op_sel_hi:[0,1,0]
	v_fma_mix_f32 v135, v7, v38, v135 op_sel:[0,1,0] op_sel_hi:[0,1,0]
	v_add_f32_dpp v12, v12, v12 row_ror:1 row_mask:0xf bank_mask:0xf bound_ctrl:1
	v_fma_mix_f32 v135, v8, v39, v135 op_sel_hi:[0,1,0]
	v_fma_mix_f32 v135, v9, v39, v135 op_sel:[0,1,0] op_sel_hi:[0,1,0]
	v_add_f32_dpp v12, v12, v12 row_ror:2 row_mask:0xf bank_mask:0xf bound_ctrl:1
	v_pk_fma_f32 v[48:49], v[96:97], v[72:73], v[6:7] op_sel_hi:[1,0,1]
	v_pk_fma_f32 v[50:51], v[98:99], v[72:73], v[8:9] op_sel_hi:[1,0,1]
	v_add_f32_dpp v12, v12, v12 row_ror:4 row_mask:0xf bank_mask:0xf bound_ctrl:1
	v_add_f32_dpp v62, v62, v65 quad_perm:[1,0,3,2] row_mask:0xf bank_mask:0xf bound_ctrl:1
	v_cvt_pk_bf16_f32 v62, v62, v62
	v_add_f32_dpp v12, v12, v12 row_ror:8 row_mask:0xf bank_mask:0xf bound_ctrl:1
	v_pk_fma_f32 v[6:7], v[92:93], v[12:13], v[48:49] op_sel_hi:[1,0,1] neg_lo:[1,0,0] neg_hi:[1,0,0]
	v_pk_fma_f32 v[8:9], v[94:95], v[12:13], v[50:51] op_sel_hi:[1,0,1] neg_lo:[1,0,0] neg_hi:[1,0,0]
	s_waitcnt lgkmcnt(0)
	s_barrier
	v_xor_b32_e32 v10, 0x10000, v10
	v_xor_b32_e32 v11, 0x1000, v11
	ds_read_b128 v[66:69], v11 offset:0
	ds_read_b128 v[20:23], v10 offset:256
	ds_read_b128 v[28:31], v10 offset:768
	ds_read_b128 v[24:27], v10 offset:512
	ds_read_b128 v[36:39], v10 offset:1280
	ds_read_b128 v[44:47], v10 offset:1792
	ds_read_b128 v[40:43], v10 offset:1536
	v_fma_mix_f32 v12, v6, v110, v180 op_sel_hi:[0,1,0]
	v_fma_mix_f32 v12, v7, v110, v12 op_sel:[0,1,0] op_sel_hi:[0,1,0]
	v_fma_mix_f32 v12, v8, v111, v12 op_sel_hi:[0,1,0]
	v_fma_mix_f32 v12, v9, v111, v12 op_sel:[0,1,0] op_sel_hi:[0,1,0]
	v_fma_mix_f32 v136, v6, v90, v180 op_sel_hi:[0,1,0]
	v_fma_mix_f32 v136, v7, v90, v136 op_sel:[0,1,0] op_sel_hi:[0,1,0]
	v_add_f32_dpp v12, v12, v12 row_ror:1 row_mask:0xf bank_mask:0xf bound_ctrl:1
	v_fma_mix_f32 v136, v8, v91, v136 op_sel_hi:[0,1,0]
	v_fma_mix_f32 v136, v9, v91, v136 op_sel:[0,1,0] op_sel_hi:[0,1,0]
	v_add_f32_dpp v12, v12, v12 row_ror:2 row_mask:0xf bank_mask:0xf bound_ctrl:1
	v_pk_fma_f32 v[48:49], v[118:119], v[72:73], v[6:7] op_sel:[0,1,0]
	v_pk_fma_f32 v[50:51], v[120:121], v[72:73], v[8:9] op_sel:[0,1,0]
	v_add_f32_dpp v12, v12, v12 row_ror:4 row_mask:0xf bank_mask:0xf bound_ctrl:1
	global_store_short v[2:3], v62, off
	v_lshl_add_u64 v[2:3], v[2:3], 0, s[84:85]
	v_add_f32_dpp v12, v12, v12 row_ror:8 row_mask:0xf bank_mask:0xf bound_ctrl:1
	v_pk_fma_f32 v[6:7], v[114:115], v[12:13], v[48:49] op_sel_hi:[1,0,1] neg_lo:[1,0,0] neg_hi:[1,0,0]
	v_pk_fma_f32 v[8:9], v[116:117], v[12:13], v[50:51] op_sel_hi:[1,0,1] neg_lo:[1,0,0] neg_hi:[1,0,0]
	v_pk_mul_f32 v[6:7], v[6:7], v[106:107]
	v_pk_mul_f32 v[8:9], v[8:9], v[108:109]
	v_fma_mix_f32 v137, v6, v112, v180 op_sel_hi:[0,1,0]
	v_fma_mix_f32 v137, v7, v112, v137 op_sel:[0,1,0] op_sel_hi:[0,1,0]
	v_fma_mix_f32 v137, v8, v113, v137 op_sel_hi:[0,1,0]
	v_fma_mix_f32 v137, v9, v113, v137 op_sel:[0,1,0] op_sel_hi:[0,1,0]
	v_add_f32_dpp v130, v130, v130 row_ror:8 row_mask:0xf bank_mask:0xc
	v_add_f32_dpp v130, v122, v122 row_ror:8 row_mask:0xf bank_mask:0x3
	v_add_f32_dpp v131, v131, v131 row_ror:8 row_mask:0xf bank_mask:0xc
	v_add_f32_dpp v131, v123, v123 row_ror:8 row_mask:0xf bank_mask:0x3
	v_add_f32_dpp v132, v132, v132 row_ror:8 row_mask:0xf bank_mask:0xc
	v_add_f32_dpp v132, v124, v124 row_ror:8 row_mask:0xf bank_mask:0x3
	v_add_f32_dpp v133, v133, v133 row_ror:8 row_mask:0xf bank_mask:0xc
	v_add_f32_dpp v133, v125, v125 row_ror:8 row_mask:0xf bank_mask:0x3
	v_add_f32_dpp v134, v134, v134 row_ror:8 row_mask:0xf bank_mask:0xc
	v_add_f32_dpp v134, v126, v126 row_ror:8 row_mask:0xf bank_mask:0x3
	v_add_f32_dpp v135, v135, v135 row_ror:8 row_mask:0xf bank_mask:0xc
	v_add_f32_dpp v135, v127, v127 row_ror:8 row_mask:0xf bank_mask:0x3
	v_add_f32_dpp v136, v136, v136 row_ror:8 row_mask:0xf bank_mask:0xc
	v_add_f32_dpp v136, v128, v128 row_ror:8 row_mask:0xf bank_mask:0x3
	v_add_f32_dpp v137, v137, v137 row_ror:8 row_mask:0xf bank_mask:0xc
	v_add_f32_dpp v137, v129, v129 row_ror:8 row_mask:0xf bank_mask:0x3
	v_add_f32_dpp v134, v134, v134 row_ror:4 row_mask:0xf bank_mask:0xa
	v_add_f32_dpp v134, v130, v130 row_ror:12 row_mask:0xf bank_mask:0x5
	v_add_f32_dpp v135, v135, v135 row_ror:4 row_mask:0xf bank_mask:0xa
	v_add_f32_dpp v135, v131, v131 row_ror:12 row_mask:0xf bank_mask:0x5
	v_add_f32_dpp v136, v136, v136 row_ror:4 row_mask:0xf bank_mask:0xa
	v_add_f32_dpp v136, v132, v132 row_ror:12 row_mask:0xf bank_mask:0x5
	v_add_f32_dpp v137, v137, v137 row_ror:4 row_mask:0xf bank_mask:0xa
	v_add_f32_dpp v137, v133, v133 row_ror:12 row_mask:0xf bank_mask:0x5
	v_cndmask_b32_e64 v62, v136, v134, s[38:39]
	v_cndmask_b32_e64 v63, v134, v136, s[38:39]
	v_cndmask_b32_e64 v64, v137, v135, s[38:39]
	v_cndmask_b32_e64 v65, v135, v137, s[38:39]
	v_add_f32_dpp v62, v63, v62 quad_perm:[2,3,0,1] row_mask:0xf bank_mask:0xf bound_ctrl:1
	s_nop 0
	v_add_f32_dpp v63, v65, v64 quad_perm:[2,3,0,1] row_mask:0xf bank_mask:0xf bound_ctrl:1
	v_cndmask_b32_e64 v65, v63, v62, s[40:41]
	v_cndmask_b32_e64 v62, v62, v63, s[40:41]
	s_nop 1
	v_add_f32_dpp v62, v62, v65 quad_perm:[1,0,3,2] row_mask:0xf bank_mask:0xf bound_ctrl:1
	v_cvt_pk_bf16_f32 v62, v62, v62
	global_store_short v[2:3], v62, off
	s_cmp_lg_u32 s28, 0x800000
	s_cbranch_scc1 .Lscan_cons_chunk
	s_setprio 0
	s_branch .LBB0_53
